# passA counted waits + LB hoist; P5/P8 rowpass g_pre hoisted, next-row copies moved to loop end
# speedup vs baseline: 1.0099x; 1.0059x over previous
; #define LAS __attribute__((address_space(3)))
; #define PA_LOADZ(r_) do { PA_DECODE(r_) (void)ch; _Pragma("unroll") for (int i = 0; i < 16; ++i) zn[i] = HZ[(tok0 + 16 * I + i) * 1024 + h * 128 + k]; } while (0)
; __device__ __forceinline__ void hgrn_passA_units(LAS unsigned char* lds, const bf16_t* HZ, const bf16_t* HVT, const float* LB, bf16_t* U, float* DC, int bid, int G, int tid) {
;     const int k = tid & 127, I = tid >> 7, lane = tid & 63, w = tid >> 6, g = lane >> 4, n = lane & 15;
;     LAS float* TOT = (LAS float*)lds;
;     LAS bf16_t* KT = (LAS bf16_t*)(lds + 2048);
;     LAS bf16_t* VS = (LAS bf16_t*)(lds + 2048 + 18432);
;     ...
;     unsigned short zn[16];
;     int r = bid;
;     if (r >= 2048) return;
;     PA_LOADZ(r);
;     for (; r < 2048; r += G) {
;         PA_DECODE(r)
;         const float lb = LB[h * 128 + k], oml = 1.0f - lb;
.LBB0_228:
	s_add_u32 s12, s52, 0x13e00000
	s_addc_u32 s13, s53, 0
	s_add_u32 s14, s52, 0x11e00000
	s_addc_u32 s15, s53, 0
	s_add_i32 s0, 0, 0x23ce0
	v_mbcnt_lo_u32_b32 v0, -1, 0
	v_mbcnt_hi_u32_b32 v0, -1, v0
	v_mov_b32_e32 v1, s0
	v_add_u32_e32 v0, s84, v0
	ds_read_b64 v[2:3], v1
	s_lshl_b32 s2, s33, 7
	s_cmpk_gt_i32 s33, 0x7ff
	s_waitcnt lgkmcnt(0)
	v_readfirstlane_b32 s11, v3
	v_readfirstlane_b32 s10, v2
	s_cbranch_scc1 .LBB0_235
	s_and_b32 s0, s2, 0x380
	s_lshl_b32 s0, s0, 1
	s_add_u32 s0, s14, s0
	s_addc_u32 s1, s15, 0
	s_ashr_i32 s4, s33, 10
	s_ashr_i32 s5, s4, 31
	v_ashrrev_i32_e32 v23, 7, v0
	s_lshl_b64 s[4:5], s[4:5], 13
	s_and_b32 s3, s92, 0x1fc0
	v_lshlrev_b32_e32 v8, 4, v23
	v_and_b32_e32 v21, 0x7f, v0
	s_or_b32 s4, s4, s3
	v_ashrrev_i32_e32 v9, 31, v8
	v_lshlrev_b32_e32 v10, 1, v21
	v_mov_b32_e32 v11, 0
	v_lshl_add_u64 v[4:5], s[4:5], 0, v[8:9]
	v_lshl_add_u64 v[2:3], s[0:1], 0, v[10:11]
	v_lshlrev_b64 v[4:5], 11, v[4:5]
	v_lshl_add_u64 v[2:3], v[2:3], 0, v[4:5]
	s_movk_i32 s0, 0x7000
	v_add_co_u32_e32 v4, vcc, s0, v2
	s_movk_i32 s0, 0x6000
	s_nop 0
	v_addc_co_u32_e32 v5, vcc, 0, v3, vcc
	v_add_co_u32_e32 v6, vcc, s0, v2
	s_movk_i32 s1, 0x4000
	s_nop 0
	v_addc_co_u32_e32 v7, vcc, 0, v3, vcc
	v_add_co_u32_e32 v12, vcc, s1, v2
	s_movk_i32 s1, 0x3000
	s_nop 0
	v_addc_co_u32_e32 v13, vcc, 0, v3, vcc
	v_add_co_u32_e32 v14, vcc, s1, v2
	s_movk_i32 s1, 0x2000
	s_nop 0
	v_addc_co_u32_e32 v15, vcc, 0, v3, vcc
	v_add_co_u32_e32 v16, vcc, s1, v2
	s_movk_i32 s1, 0x1000
	s_nop 0
	v_addc_co_u32_e32 v17, vcc, 0, v3, vcc
	v_add_co_u32_e32 v18, vcc, s1, v2
	s_movk_i32 s0, 0x5000
	s_nop 0
	v_addc_co_u32_e32 v19, vcc, 0, v3, vcc
	s_and_b32 s30, s2, 0x380
	v_or_b32_e32 v110, s30, v21
	v_lshlrev_b32_e32 v110, 2, v110
	global_load_dword v110, v110, s[72:73]
	global_load_ushort v20, v[2:3], off offset:2048
	global_load_ushort v22, v[2:3], off
	global_load_ushort v39, v[12:13], off offset:2048
	global_load_ushort v35, v[14:15], off offset:2048
	global_load_ushort v31, v[16:17], off offset:2048
	global_load_ushort v27, v[18:19], off offset:2048
	global_load_ushort v26, v[18:19], off
	global_load_ushort v30, v[16:17], off
	global_load_ushort v34, v[14:15], off
	global_load_ushort v38, v[12:13], off
	v_add_co_u32_e32 v2, vcc, s0, v2
	v_lshlrev_b32_e32 v1, 3, v0
	s_nop 0
	v_addc_co_u32_e32 v3, vcc, 0, v3, vcc
	global_load_ushort v42, v[2:3], off
	global_load_ushort v43, v[2:3], off offset:2048
	global_load_ushort v71, v[6:7], off
	global_load_ushort v70, v[6:7], off offset:2048
	global_load_ushort v47, v[4:5], off
	global_load_ushort v46, v[4:5], off offset:2048
	v_lshl_add_u64 v[12:13], s[14:15], 0, v[10:11]
	v_lshl_add_u32 v50, v21, 2, 0
	s_movk_i32 s3, 0x8c
	v_ashrrev_i32_e32 v10, 2, v0
	v_bfe_u32 v5, v0, 4, 2
	v_and_b32_e32 v2, 56, v1
	v_mov_b32_e32 v1, v11
	v_mad_u32_u24 v6, v21, s3, v50
	s_movk_i32 s3, 0x80
	v_and_b32_e32 v4, -16, v10
	v_and_b32_e32 v3, 15, v0
	v_ashrrev_i32_e32 v48, 3, v0
	v_lshl_add_u32 v49, v0, 2, 0
	v_cmp_gt_u32_e64 s[6:7], s3, v0
	v_lshl_add_u64 v[14:15], v[0:1], 2, s[36:37]
	v_bfi_b32 v16, -16, v10, v0
	v_lshlrev_b32_e32 v10, 3, v5
	v_lshl_add_u32 v0, v5, 4, 0
	v_ashrrev_i32_e32 v5, 31, v4
	v_lshl_add_u32 v1, v2, 1, 0
	s_movk_i32 s3, 0x90
	v_lshl_add_u64 v[4:5], v[4:5], 1, s[10:11]
	v_cmp_lt_i32_e64 s[0:1], 0, v23
	v_cmp_lt_i32_e64 s[8:9], 1, v23
	v_cmp_lt_i32_e64 s[4:5], 2, v23
	v_lshlrev_b32_e32 v7, 5, v23
	v_mad_u64_u32 v[16:17], s[18:19], v16, s3, v[0:1]
	v_lshl_add_u64 v[4:5], v[4:5], 0, v[10:11]
	v_mul_lo_u32 v23, v48, s3
	v_mul_u32_u24_e32 v24, 0x90, v3
	v_lshlrev_b32_e32 v10, 8, v3
	s_add_i32 s3, s33, s54
	s_mov_b32 s17, 0
	v_lshl_add_u64 v[18:19], v[4:5], 0, v[10:11]
	s_lshl_b32 s3, s3, 3
	s_lshl_b32 s22, s54, 7
	v_lshlrev_b32_e32 v10, 1, v2
	s_mov_b32 s23, 0x800000
	s_mov_b32 s24, 0x3f317217
	s_mov_b32 s25, 0x7f800000
	v_add_u32_e32 v17, v6, v7
	v_add_u32_e32 v51, v1, v23
	v_add_u32_e32 v52, v0, v24
	v_mov_b32_e32 v53, 0x41b17218
	s_mov_b32 s26, s2
	s_mov_b32 s20, s33
	s_waitcnt vmcnt(15)
	v_mov_b32_e32 v55, v20
	s_waitcnt vmcnt(14)
	v_mov_b32_e32 v54, v22
	s_waitcnt vmcnt(13)
	v_mov_b32_e32 v63, v39
	s_waitcnt vmcnt(12)
	v_mov_b32_e32 v61, v35
	s_waitcnt vmcnt(11)
	v_mov_b32_e32 v59, v31
	s_waitcnt vmcnt(10)
	v_mov_b32_e32 v57, v27
	s_waitcnt vmcnt(9)
	v_mov_b32_e32 v56, v26
	s_waitcnt vmcnt(8)
	v_mov_b32_e32 v58, v30
	s_waitcnt vmcnt(7)
	v_mov_b32_e32 v60, v34
	s_waitcnt vmcnt(6)
	v_mov_b32_e32 v62, v38
	s_waitcnt vmcnt(5)
	v_mov_b32_e32 v64, v42
	s_waitcnt vmcnt(4)
	v_mov_b32_e32 v65, v43
	s_waitcnt vmcnt(3)
	v_mov_b32_e32 v66, v71
	s_waitcnt vmcnt(2)
	v_mov_b32_e32 v67, v70
	s_waitcnt vmcnt(1)
	v_mov_b32_e32 v68, v47
	s_waitcnt vmcnt(0)
	v_mov_b32_e32 v69, v46
	s_branch .LBB0_231
; __device__ __forceinline__ void hgrn_passA_units(LAS unsigned char* lds, const bf16_t* HZ, const bf16_t* HVT, const float* LB, bf16_t* U, float* DC, int bid, int G, int tid) {
;     ...
;         const float lb = LB[h * 128 + k], oml = 1.0f - lb;
;         unsigned short zc[16];
; #pragma unroll
;         for (int i = 0; i < 16; ++i) zc[i] = zn[i];
;         u32x4 vst[2];
; #pragma unroll
;         for (int ps = 0; ps < 2; ++ps) vst[ps] = *(const u32x4*)(HVT + (size_t)(h * 128 + 64 * ps + (tid >> 3)) * T + tok0 + 8 * (tid & 7));
;         if (r + G < 2048) PA_LOADZ(r + G);
;         float cs[16], kk[16]; float run = 0.f;
; #pragma unroll
;         for (int i = 0; i < 16; ++i) {
;             const float z = bf2f(zc[i]);
;             const float e = __expf(-z), s = __builtin_amdgcn_rcpf(1.0f + e);
;             run += __logf(lb + oml * s); cs[i] = run; kk[i] = oml * e * s;
;         }
;         TOT[I * 128 + k] = run;
;         LDS_BAR;
;         const float t0 = TOT[k], t1 = TOT[128 + k], t2 = TOT[256 + k], t3 = TOT[384 + k];
;         const float rI = (I > 0 ? t0 : 0.f) + (I > 1 ? t1 : 0.f) + (I > 2 ? t2 : 0.f);
;         const float blast = (t0 + t1) + (t2 + t3);
;         unsigned pw[8];
; #pragma unroll
;         for (int i = 0; i < 8; ++i) pw[i] = pk2(kk[2 * i] * __expf(blast - rI - cs[2 * i]), kk[2 * i + 1] * __expf(blast - rI - cs[2 * i + 1]));
;         LAS u32x4* kd = (LAS u32x4*)(KT + k * 72 + 16 * I);
;         kd[0] = (u32x4){pw[0], pw[1], pw[2], pw[3]}; kd[1] = (u32x4){pw[4], pw[5], pw[6], pw[7]};
;         if (I == 0) DC[(size_t)ch * 128 + k] = __expf(blast);
; #pragma unroll
;         for (int ps = 0; ps < 2; ++ps) *(LAS u32x4*)(VS + (64 * ps + (tid >> 3)) * 72 + 8 * (tid & 7)) = vst[ps];
;         LDS_BAR;
;         f32x4 acc[8];
; #pragma unroll
;         for (int d = 0; d < 8; ++d) acc[d] = (f32x4){0.f, 0.f, 0.f, 0.f};
; #pragma unroll
;         for (int st = 0; st < 2; ++st) {
;             const bf16x8 a = *(const LAS bf16x8*)(KT + (16 * w + n) * 72 + 32 * st + 8 * g);
; #pragma unroll
;             for (int d = 0; d < 8; ++d) acc[d] = mfma16(a, *(const LAS bf16x8*)(VS + (16 * d + n) * 72 + 32 * st + 8 * g), acc[d]);
;         }
; #pragma unroll
;         for (int d = 0; d < 8; ++d) { u32x2 o; o.x = pk2(acc[d][0], acc[d][1]); o.y = pk2(acc[d][2], acc[d][3]); *(u32x2*)(U + (size_t)ch * 16384 + (size_t)(16 * d + n) * 128 + 16 * w + 4 * g) = o; }
.LBB0_230:
	s_or_b64 exec, exec, s[20:21]
	s_waitcnt vmcnt(17)
	ds_write_b128 v51, v[0:3] offset:20480
	s_waitcnt vmcnt(16)
	ds_write_b128 v51, v[4:7] offset:29696
	s_waitcnt lgkmcnt(0)
	s_barrier
	ds_read_b128 v[0:3], v16 offset:2048
	ds_read_b128 v[4:7], v52 offset:20480
	ds_read_b128 v[22:25], v16 offset:2112
	ds_read_b128 v[26:29], v52 offset:20544
	s_waitcnt lgkmcnt(2)
	v_mfma_f32_16x16x32_bf16 v[4:7], v[0:3], v[4:7], 0
	ds_read_b128 v[30:33], v52 offset:22784
	ds_read_b128 v[34:37], v52 offset:22848
	ds_read_b128 v[38:41], v52 offset:25088
	ds_read_b128 v[42:45], v52 offset:25152
	ds_read_b128 v[70:73], v52 offset:27392
	ds_read_b128 v[74:77], v52 offset:27456
	s_waitcnt lgkmcnt(5)
	v_mfma_f32_16x16x32_bf16 v[30:33], v[0:3], v[30:33], 0
	ds_read_b128 v[78:81], v52 offset:29696
	ds_read_b128 v[82:85], v52 offset:29760
	ds_read_b128 v[86:89], v52 offset:32000
	ds_read_b128 v[90:93], v52 offset:32064
	s_lshl_b64 s[10:11], s[10:11], 15
	v_mfma_f32_16x16x32_bf16 v[4:7], v[22:25], v[26:29], v[4:7]
	v_lshl_add_u64 v[46:47], v[18:19], 0, s[10:11]
	ds_read_b128 v[94:97], v52 offset:34304
	ds_read_b128 v[98:101], v52 offset:34368
	ds_read_b128 v[102:105], v52 offset:36608
	ds_read_b128 v[106:109], v52 offset:36672
	s_waitcnt lgkmcnt(9)
	v_mfma_f32_16x16x32_bf16 v[70:73], v[0:3], v[70:73], 0
	s_nop 0
	v_cvt_pk_bf16_f32 v26, v4, v5
	v_cvt_pk_bf16_f32 v27, v6, v7
	global_store_dwordx2 v[46:47], v[26:27], off
	v_mfma_f32_16x16x32_bf16 v[4:7], v[22:25], v[34:37], v[30:33]
	s_add_i32 s3, s3, s50
	s_add_i32 s26, s26, s22
	s_waitcnt vmcnt(1)
	v_mov_b32_e32 v20, v55
	v_mfma_f32_16x16x32_bf16 v[38:41], v[0:3], v[38:41], 0
	v_add_co_u32_e32 v32, vcc, 0x1000, v46
	s_nop 2
	v_cvt_pk_bf16_f32 v30, v4, v5
	s_waitcnt lgkmcnt(7)
	v_mfma_f32_16x16x32_bf16 v[78:81], v[0:3], v[78:81], 0
	v_cvt_pk_bf16_f32 v31, v6, v7
	v_addc_co_u32_e32 v33, vcc, 0, v47, vcc
	v_mfma_f32_16x16x32_bf16 v[4:7], v[22:25], v[74:77], v[70:73]
	global_store_dwordx2 v[32:33], v[30:31], off
	s_mov_b32 s20, s27
	s_waitcnt lgkmcnt(5)
	v_mfma_f32_16x16x32_bf16 v[86:89], v[0:3], v[86:89], 0
	v_mov_b32_e32 v71, v66
	s_nop 2
	v_cvt_pk_bf16_f32 v4, v4, v5
	v_cvt_pk_bf16_f32 v5, v6, v7
	v_mfma_f32_16x16x32_bf16 v[26:29], v[22:25], v[42:45], v[38:41]
	v_mov_b32_e32 v42, v64
	v_mov_b32_e32 v43, v65
	v_mov_b32_e32 v70, v67
	v_add_co_u32_e32 v40, vcc, 0x2000, v46
	v_mfma_f32_16x16x32_bf16 v[30:33], v[22:25], v[82:85], v[78:81]
	s_nop 0
	v_addc_co_u32_e32 v41, vcc, 0, v47, vcc
	v_add_co_u32_e32 v6, vcc, 0x3000, v46
	s_waitcnt lgkmcnt(3)
	v_mfma_f32_16x16x32_bf16 v[94:97], v[0:3], v[94:97], 0
	v_cvt_pk_bf16_f32 v38, v26, v27
	v_cvt_pk_bf16_f32 v39, v28, v29
	v_addc_co_u32_e32 v7, vcc, 0, v47, vcc
	s_waitcnt lgkmcnt(1)
	v_mfma_f32_16x16x32_bf16 v[0:3], v[0:3], v[102:105], 0
	global_store_dwordx2 v[6:7], v[4:5], off
	v_add_co_u32_e32 v6, vcc, 0x4000, v46
	v_mfma_f32_16x16x32_bf16 v[26:29], v[22:25], v[90:93], v[86:89]
	v_cvt_pk_bf16_f32 v4, v30, v31
	v_cvt_pk_bf16_f32 v5, v32, v33
	v_addc_co_u32_e32 v7, vcc, 0, v47, vcc
	s_waitcnt lgkmcnt(0)
	v_mfma_f32_16x16x32_bf16 v[0:3], v[22:25], v[106:109], v[0:3]
	global_store_dwordx2 v[6:7], v[4:5], off
	v_add_co_u32_e32 v6, vcc, 0x5000, v46
	v_mfma_f32_16x16x32_bf16 v[34:37], v[22:25], v[98:101], v[94:97]
	v_cvt_pk_bf16_f32 v4, v26, v27
	v_cvt_pk_bf16_f32 v5, v28, v29
	v_addc_co_u32_e32 v7, vcc, 0, v47, vcc
	global_store_dwordx2 v[6:7], v[4:5], off
	v_add_co_u32_e32 v6, vcc, 0x6000, v46
	v_cvt_pk_bf16_f32 v0, v0, v1
	s_nop 0
	v_addc_co_u32_e32 v7, vcc, 0, v47, vcc
	v_cvt_pk_bf16_f32 v1, v2, v3
	v_add_co_u32_e32 v2, vcc, 0x7000, v46
	v_cvt_pk_bf16_f32 v4, v34, v35
	v_cvt_pk_bf16_f32 v5, v36, v37
	v_addc_co_u32_e32 v3, vcc, 0, v47, vcc
	global_store_dwordx2 v[40:41], v[38:39], off
	global_store_dwordx2 v[6:7], v[4:5], off
	global_store_dwordx2 v[2:3], v[0:1], off
	s_waitcnt lgkmcnt(0)
	s_barrier
	s_andn2_b64 vcc, exec, s[18:19]
	v_mov_b32_e32 v22, v54
	v_mov_b32_e32 v26, v56
	v_mov_b32_e32 v27, v57
	v_mov_b32_e32 v30, v58
	v_mov_b32_e32 v31, v59
	v_mov_b32_e32 v34, v60
	v_mov_b32_e32 v35, v61
	v_mov_b32_e32 v38, v62
	v_mov_b32_e32 v39, v63
	v_mov_b32_e32 v47, v68
	v_mov_b32_e32 v46, v69
	s_cbranch_vccz .LBB0_235
.LBB0_231:
	s_ashr_i32 s10, s20, 10
	s_ashr_i32 s11, s10, 31
	s_bfe_u32 s21, s20, 0x70003
	s_and_b32 s28, s26, 0x380
	s_lshl_b64 s[10:11], s[10:11], 14
	s_add_u32 s10, s12, s10
	s_addc_u32 s11, s13, s11
	s_lshl_b32 s16, s21, 7
	v_add_u32_e32 v0, s28, v48
	s_add_u32 s10, s10, s16
	s_addc_u32 s11, s11, 0
	v_ashrrev_i32_e32 v1, 31, v0
	v_lshl_add_u64 v[2:3], s[10:11], 0, v[10:11]
	v_lshlrev_b64 v[0:1], 15, v[0:1]
	v_lshl_add_u64 v[0:1], v[2:3], 0, v[0:1]
	v_add_co_u32_e32 v4, vcc, 0x200000, v0
	s_add_i32 s27, s20, s54
	s_nop 0
	v_addc_co_u32_e32 v5, vcc, 0, v1, vcc
	global_load_dwordx4 v[0:3], v[0:1], off
	s_nop 0
	global_load_dwordx4 v[4:7], v[4:5], off
	s_cmpk_gt_i32 s27, 0x7ff
	s_cselect_b64 s[18:19], -1, 0
	s_and_b64 vcc, exec, s[18:19]
	s_and_b32 s16, s3, 0x1fc0
	v_lshl_add_u64 v[24:25], s[16:17], 0, v[8:9]
	s_add_i32 s16, s22, s26
	s_ashr_i32 s10, s27, 10
	s_and_b32 s16, s16, 0x380
	s_ashr_i32 s11, s10, 31
	s_lshl_b32 s16, s16, 1
	v_lshl_add_u64 v[28:29], v[12:13], 0, s[16:17]
	s_lshl_b64 s[10:11], s[10:11], 24
	v_lshlrev_b64 v[24:25], 11, v[24:25]
	v_lshl_add_u64 v[28:29], v[28:29], 0, s[10:11]
	v_lshl_add_u64 v[24:25], v[28:29], 0, v[24:25]
	v_add_co_u32_e32 v28, vcc, 0x1000, v24
	s_nop 1
	v_addc_co_u32_e32 v29, vcc, 0, v25, vcc
	v_add_co_u32_e32 v32, vcc, 0x2000, v24
	s_nop 1
	v_addc_co_u32_e32 v33, vcc, 0, v25, vcc
	v_add_co_u32_e32 v36, vcc, 0x3000, v24
	s_nop 1
	v_addc_co_u32_e32 v37, vcc, 0, v25, vcc
	global_load_ushort v54, v[24:25], off
	global_load_ushort v55, v[24:25], off offset:2048
	global_load_ushort v56, v[28:29], off
	global_load_ushort v57, v[28:29], off offset:2048
	global_load_ushort v58, v[32:33], off
	global_load_ushort v59, v[32:33], off offset:2048
	global_load_ushort v60, v[36:37], off
	global_load_ushort v61, v[36:37], off offset:2048
	v_add_co_u32_e32 v28, vcc, 0x4000, v24
	s_nop 1
	v_addc_co_u32_e32 v29, vcc, 0, v25, vcc
	v_add_co_u32_e32 v32, vcc, 0x5000, v24
	s_nop 1
	v_addc_co_u32_e32 v33, vcc, 0, v25, vcc
	v_add_co_u32_e32 v36, vcc, 0x6000, v24
	s_nop 1
	v_addc_co_u32_e32 v37, vcc, 0, v25, vcc
	v_add_co_u32_e32 v24, vcc, 0x7000, v24
	s_nop 1
	v_addc_co_u32_e32 v25, vcc, 0, v25, vcc
	global_load_ushort v62, v[28:29], off
	global_load_ushort v63, v[28:29], off offset:2048
	global_load_ushort v64, v[32:33], off
	global_load_ushort v65, v[32:33], off offset:2048
	global_load_ushort v66, v[36:37], off
	global_load_ushort v67, v[36:37], off offset:2048
	global_load_ushort v68, v[24:25], off
	global_load_ushort v69, v[24:25], off offset:2048
; __device__ __forceinline__ void hgrn_passA_units(LAS unsigned char* lds, const bf16_t* HZ, const bf16_t* HVT, const float* LB, bf16_t* U, float* DC, int bid, int G, int tid) {
;     ...
;         float cs[16], kk[16]; float run = 0.f;
; #pragma unroll
;         for (int i = 0; i < 16; ++i) {
;             const float z = bf2f(zc[i]);
;             const float e = __expf(-z), s = __builtin_amdgcn_rcpf(1.0f + e);
;             run += __logf(lb + oml * s); cs[i] = run; kk[i] = oml * e * s;
;         }
;         TOT[I * 128 + k] = run;
.LBB0_233:
	v_lshlrev_b32_e32 v22, 16, v22
	v_mul_f32_e32 v22, 0xbfb8aa3b, v22
	v_exp_f32_e32 v22, v22
	v_lshlrev_b32_e32 v20, 16, v20
	v_mul_f32_e32 v20, 0xbfb8aa3b, v20
	v_exp_f32_e32 v23, v20
	v_add_f32_e32 v20, 1.0, v22
	v_rcp_f32_e32 v24, v20
	v_sub_f32_e32 v20, 1.0, v110
	v_add_f32_e32 v25, 1.0, v23
	v_rcp_f32_e32 v25, v25
	v_fma_f32 v28, v24, v20, v110
	v_cmp_gt_f32_e32 vcc, s23, v28
	v_lshlrev_b32_e32 v26, 16, v26
	v_mul_f32_e32 v26, 0xbfb8aa3b, v26
	v_cndmask_b32_e64 v29, 0, 32, vcc
	v_ldexp_f32 v28, v28, v29
	v_log_f32_e32 v28, v28
	v_fma_f32 v29, v25, v20, v110
	v_exp_f32_e32 v26, v26
	v_lshlrev_b32_e32 v27, 16, v27
	v_mul_f32_e32 v32, 0x3f317217, v28
	v_fma_f32 v32, v28, s24, -v32
	v_fmac_f32_e32 v32, 0x3377d1cf, v28
	v_fmac_f32_e32 v32, 0x3f317217, v28
	v_cmp_lt_f32_e64 s[10:11], |v28|, s25
	v_mul_f32_e32 v27, 0xbfb8aa3b, v27
	v_exp_f32_e32 v27, v27
	v_cndmask_b32_e64 v28, v28, v32, s[10:11]
	v_cmp_gt_f32_e64 s[10:11], s23, v29
	v_lshlrev_b32_e32 v30, 16, v30
	v_mul_f32_e32 v30, 0xbfb8aa3b, v30
	v_cndmask_b32_e64 v32, 0, 32, s[10:11]
	v_ldexp_f32 v29, v29, v32
	v_log_f32_e32 v29, v29
	v_cndmask_b32_e32 v32, 0, v53, vcc
	v_sub_f32_e32 v28, v28, v32
	v_add_f32_e32 v86, 0, v28
	v_mul_f32_e32 v28, 0x3f317217, v29
	v_fma_f32 v28, v29, s24, -v28
	v_fmac_f32_e32 v28, 0x3377d1cf, v29
	v_fmac_f32_e32 v28, 0x3f317217, v29
	v_cmp_lt_f32_e64 vcc, |v29|, s25
	v_cndmask_b32_e64 v32, 0, v53, s[10:11]
	v_exp_f32_e32 v30, v30
	v_cndmask_b32_e32 v29, v29, v28, vcc
	v_add_f32_e32 v28, 1.0, v26
	v_rcp_f32_e32 v28, v28
	v_sub_f32_e32 v29, v29, v32
	v_add_f32_e32 v87, v29, v86
	v_lshlrev_b32_e32 v31, 16, v31
	v_fma_f32 v29, v28, v20, v110
	v_cmp_gt_f32_e32 vcc, s23, v29
	v_mul_f32_e32 v31, 0xbfb8aa3b, v31
	v_exp_f32_e32 v31, v31
	v_cndmask_b32_e64 v32, 0, 32, vcc
	v_ldexp_f32 v29, v29, v32
	v_log_f32_e32 v32, v29
	v_lshlrev_b32_e32 v34, 16, v34
	v_mul_f32_e32 v34, 0xbfb8aa3b, v34
	v_exp_f32_e32 v34, v34
	v_mul_f32_e32 v29, 0x3f317217, v32
	v_fma_f32 v33, v32, s24, -v29
	v_add_f32_e32 v29, 1.0, v27
	v_rcp_f32_e32 v29, v29
	v_fmac_f32_e32 v33, 0x3377d1cf, v32
	v_fmac_f32_e32 v33, 0x3f317217, v32
	v_cmp_lt_f32_e64 s[10:11], |v32|, s25
	v_lshlrev_b32_e32 v35, 16, v35
	v_mul_f32_e32 v35, 0xbfb8aa3b, v35
	v_cndmask_b32_e64 v32, v32, v33, s[10:11]
	v_fma_f32 v33, v29, v20, v110
	v_cmp_gt_f32_e64 s[10:11], s23, v33
	v_exp_f32_e32 v35, v35
	v_lshlrev_b32_e32 v38, 16, v38
	v_cndmask_b32_e64 v36, 0, 32, s[10:11]
	v_ldexp_f32 v33, v33, v36
	v_log_f32_e32 v33, v33
	v_cndmask_b32_e32 v36, 0, v53, vcc
	v_sub_f32_e32 v32, v32, v36
	v_add_f32_e32 v88, v32, v87
	v_mul_f32_e32 v32, 0x3f317217, v33
	v_fma_f32 v32, v33, s24, -v32
	v_fmac_f32_e32 v32, 0x3377d1cf, v33
	v_fmac_f32_e32 v32, 0x3f317217, v33
	v_cmp_lt_f32_e64 vcc, |v33|, s25
	v_cndmask_b32_e64 v36, 0, v53, s[10:11]
	v_mul_f32_e32 v38, 0xbfb8aa3b, v38
	v_cndmask_b32_e32 v33, v33, v32, vcc
	v_add_f32_e32 v32, 1.0, v30
	v_rcp_f32_e32 v32, v32
	v_sub_f32_e32 v33, v33, v36
	v_add_f32_e32 v89, v33, v88
	v_exp_f32_e32 v38, v38
	v_fma_f32 v33, v32, v20, v110
	v_cmp_gt_f32_e32 vcc, s23, v33
	v_lshlrev_b32_e32 v39, 16, v39
	v_mul_f32_e32 v39, 0xbfb8aa3b, v39
	v_cndmask_b32_e64 v36, 0, 32, vcc
	v_ldexp_f32 v33, v33, v36
	v_log_f32_e32 v36, v33
	v_exp_f32_e32 v39, v39
	v_lshlrev_b32_e32 v42, 16, v42
	v_mul_f32_e32 v42, 0xbfb8aa3b, v42
	v_mul_f32_e32 v33, 0x3f317217, v36
	v_fma_f32 v37, v36, s24, -v33
	v_add_f32_e32 v33, 1.0, v31
	v_rcp_f32_e32 v33, v33
	v_fmac_f32_e32 v37, 0x3377d1cf, v36
	v_fmac_f32_e32 v37, 0x3f317217, v36
	v_cmp_lt_f32_e64 s[10:11], |v36|, s25
	v_exp_f32_e32 v42, v42
	v_lshlrev_b32_e32 v43, 16, v43
	v_cndmask_b32_e64 v36, v36, v37, s[10:11]
	v_fma_f32 v37, v33, v20, v110
	v_cmp_gt_f32_e64 s[10:11], s23, v37
	v_mul_f32_e32 v43, 0xbfb8aa3b, v43
	v_exp_f32_e32 v43, v43
	v_cndmask_b32_e64 v40, 0, 32, s[10:11]
	v_ldexp_f32 v37, v37, v40
	v_log_f32_e32 v37, v37
	v_cndmask_b32_e32 v40, 0, v53, vcc
	v_sub_f32_e32 v36, v36, v40
	v_add_f32_e32 v90, v36, v89
	v_mul_f32_e32 v36, 0x3f317217, v37
	v_fma_f32 v36, v37, s24, -v36
	v_fmac_f32_e32 v36, 0x3377d1cf, v37
	v_fmac_f32_e32 v36, 0x3f317217, v37
	v_cmp_lt_f32_e64 vcc, |v37|, s25
	v_cndmask_b32_e64 v40, 0, v53, s[10:11]
	v_lshlrev_b32_e32 v71, 16, v71
	v_cndmask_b32_e32 v37, v37, v36, vcc
	v_add_f32_e32 v36, 1.0, v34
	v_rcp_f32_e32 v36, v36
	v_sub_f32_e32 v37, v37, v40
	v_add_f32_e32 v91, v37, v90
	v_mul_f32_e32 v71, 0xbfb8aa3b, v71
	v_fma_f32 v37, v36, v20, v110
	v_cmp_gt_f32_e32 vcc, s23, v37
	v_lshlrev_b32_e32 v70, 16, v70
	v_mul_f32_e32 v70, 0xbfb8aa3b, v70
	v_cndmask_b32_e64 v40, 0, 32, vcc
	v_ldexp_f32 v37, v37, v40
	v_log_f32_e32 v40, v37
	v_lshlrev_b32_e32 v47, 16, v47
	v_mul_f32_e32 v47, 0xbfb8aa3b, v47
	v_lshlrev_b32_e32 v46, 16, v46
	v_mul_f32_e32 v37, 0x3f317217, v40
	v_fma_f32 v41, v40, s24, -v37
	v_add_f32_e32 v37, 1.0, v35
	v_rcp_f32_e32 v37, v37
	v_fmac_f32_e32 v41, 0x3377d1cf, v40
	v_fmac_f32_e32 v41, 0x3f317217, v40
	v_cmp_lt_f32_e64 s[10:11], |v40|, s25
	v_mul_f32_e32 v46, 0xbfb8aa3b, v46
	v_pk_mul_f32 v[22:23], v[22:23], v[20:21] op_sel_hi:[1,0]
	v_cndmask_b32_e64 v40, v40, v41, s[10:11]
	v_fma_f32 v41, v37, v20, v110
	v_cmp_gt_f32_e64 s[10:11], s23, v41
	v_pk_mul_f32 v[22:23], v[24:25], v[22:23]
	v_pk_mul_f32 v[26:27], v[26:27], v[20:21] op_sel_hi:[1,0]
	v_cndmask_b32_e64 v44, 0, 32, s[10:11]
	v_ldexp_f32 v41, v41, v44
	v_log_f32_e32 v41, v41
	v_cndmask_b32_e32 v44, 0, v53, vcc
	v_sub_f32_e32 v40, v40, v44
	v_add_f32_e32 v92, v40, v91
	v_mul_f32_e32 v40, 0x3f317217, v41
	v_fma_f32 v40, v41, s24, -v40
	v_fmac_f32_e32 v40, 0x3377d1cf, v41
	v_fmac_f32_e32 v40, 0x3f317217, v41
	v_cmp_lt_f32_e64 vcc, |v41|, s25
	v_cndmask_b32_e64 v44, 0, v53, s[10:11]
; #define LDS_BAR do { asm volatile("s_waitcnt lgkmcnt(0)" ::: "memory"); __builtin_amdgcn_s_barrier(); asm volatile("" ::: "memory"); } while (0)
; __device__ __forceinline__ void hgrn_passA_units(LAS unsigned char* lds, const bf16_t* HZ, const bf16_t* HVT, const float* LB, bf16_t* U, float* DC, int bid, int G, int tid) {
;     ...
;         float cs[16], kk[16]; float run = 0.f;
; #pragma unroll
;         for (int i = 0; i < 16; ++i) {
;             const float z = bf2f(zc[i]);
;             const float e = __expf(-z), s = __builtin_amdgcn_rcpf(1.0f + e);
;             run += __logf(lb + oml * s); cs[i] = run; kk[i] = oml * e * s;
;         }
;         TOT[I * 128 + k] = run;
;         LDS_BAR;
	v_pk_mul_f32 v[26:27], v[28:29], v[26:27]
	v_cndmask_b32_e32 v41, v41, v40, vcc
	v_add_f32_e32 v40, 1.0, v38
	v_rcp_f32_e32 v40, v40
	v_sub_f32_e32 v41, v41, v44
	v_add_f32_e32 v93, v41, v92
	v_pk_mul_f32 v[28:29], v[34:35], v[20:21] op_sel_hi:[1,0]
	v_fma_f32 v41, v40, v20, v110
	v_cmp_gt_f32_e32 vcc, s23, v41
	v_pk_mul_f32 v[28:29], v[36:37], v[28:29]
	s_nop 0
	v_cndmask_b32_e64 v44, 0, 32, vcc
	v_ldexp_f32 v41, v41, v44
	v_log_f32_e32 v44, v41
	s_nop 0
	v_mul_f32_e32 v41, 0x3f317217, v44
	v_fma_f32 v45, v44, s24, -v41
	v_add_f32_e32 v41, 1.0, v39
	v_rcp_f32_e32 v41, v41
	v_fmac_f32_e32 v45, 0x3377d1cf, v44
	v_fmac_f32_e32 v45, 0x3f317217, v44
	v_cmp_lt_f32_e64 s[10:11], |v44|, s25
	s_nop 1
	v_cndmask_b32_e64 v44, v44, v45, s[10:11]
	v_fma_f32 v45, v41, v20, v110
	v_cmp_gt_f32_e64 s[10:11], s23, v45
	s_nop 1
	v_cndmask_b32_e64 v73, 0, 32, s[10:11]
	v_ldexp_f32 v45, v45, v73
	v_log_f32_e32 v45, v45
	v_cndmask_b32_e32 v73, 0, v53, vcc
	v_sub_f32_e32 v44, v44, v73
	v_add_f32_e32 v94, v44, v93
	v_mul_f32_e32 v44, 0x3f317217, v45
	v_fma_f32 v44, v45, s24, -v44
	v_fmac_f32_e32 v44, 0x3377d1cf, v45
	v_fmac_f32_e32 v44, 0x3f317217, v45
	v_cmp_lt_f32_e64 vcc, |v45|, s25
	v_cndmask_b32_e64 v73, 0, v53, s[10:11]
	s_nop 0
	v_cndmask_b32_e32 v45, v45, v44, vcc
	v_add_f32_e32 v44, 1.0, v42
	v_rcp_f32_e32 v44, v44
	v_sub_f32_e32 v45, v45, v73
	v_add_f32_e32 v95, v45, v94
	v_fma_f32 v45, v44, v20, v110
	v_cmp_gt_f32_e32 vcc, s23, v45
	s_nop 1
	v_cndmask_b32_e64 v73, 0, 32, vcc
	v_ldexp_f32 v45, v45, v73
	v_log_f32_e32 v73, v45
	s_nop 0
	v_mul_f32_e32 v45, 0x3f317217, v73
	v_fma_f32 v74, v73, s24, -v45
	v_add_f32_e32 v45, 1.0, v43
	v_rcp_f32_e32 v45, v45
	v_fmac_f32_e32 v74, 0x3377d1cf, v73
	v_fmac_f32_e32 v74, 0x3f317217, v73
	v_cmp_lt_f32_e64 s[10:11], |v73|, s25
	s_nop 1
	v_cndmask_b32_e64 v73, v73, v74, s[10:11]
	v_fma_f32 v74, v20, v45, v110
	v_cmp_gt_f32_e64 s[10:11], s23, v74
	s_nop 1
	v_cndmask_b32_e64 v75, 0, 32, s[10:11]
	v_ldexp_f32 v74, v74, v75
	v_log_f32_e32 v75, v74
	v_cndmask_b32_e32 v74, 0, v53, vcc
	v_sub_f32_e32 v73, v73, v74
	v_add_f32_e32 v96, v73, v95
	v_mul_f32_e32 v73, 0x3f317217, v75
	v_exp_f32_e32 v74, v71
	v_fma_f32 v73, v75, s24, -v73
	v_fmac_f32_e32 v73, 0x3377d1cf, v75
	v_fmac_f32_e32 v73, 0x3f317217, v75
	v_cmp_lt_f32_e64 vcc, |v75|, s25
	s_nop 1
	v_cndmask_b32_e32 v71, v75, v73, vcc
	v_add_f32_e32 v73, 1.0, v74
	v_rcp_f32_e32 v76, v73
	v_cndmask_b32_e64 v73, 0, v53, s[10:11]
	v_sub_f32_e32 v71, v71, v73
	v_add_f32_e32 v97, v71, v96
	v_fma_f32 v71, v20, v76, v110
	v_cmp_gt_f32_e32 vcc, s23, v71
	v_exp_f32_e32 v75, v70
	s_nop 0
	v_cndmask_b32_e64 v73, 0, 32, vcc
	v_ldexp_f32 v71, v71, v73
	v_log_f32_e32 v71, v71
	v_add_f32_e32 v73, 1.0, v75
	v_rcp_f32_e32 v77, v73
	v_mul_f32_e32 v70, 0x3f317217, v71
	v_fma_f32 v70, v71, s24, -v70
	v_fmac_f32_e32 v70, 0x3377d1cf, v71
	v_fmac_f32_e32 v70, 0x3f317217, v71
	v_cmp_lt_f32_e64 s[10:11], |v71|, s25
	s_nop 1
	v_cndmask_b32_e64 v70, v71, v70, s[10:11]
	v_fma_f32 v71, v20, v77, v110
	v_cmp_gt_f32_e64 s[10:11], s23, v71
	s_nop 1
	v_cndmask_b32_e64 v73, 0, 32, s[10:11]
	v_ldexp_f32 v71, v71, v73
	v_log_f32_e32 v71, v71
	v_cndmask_b32_e32 v73, 0, v53, vcc
	v_sub_f32_e32 v70, v70, v73
	v_add_f32_e32 v98, v70, v97
	v_mul_f32_e32 v70, 0x3f317217, v71
	v_fma_f32 v73, v71, s24, -v70
	v_exp_f32_e32 v70, v47
	v_fmac_f32_e32 v73, 0x3377d1cf, v71
	v_fmac_f32_e32 v73, 0x3f317217, v71
	v_cmp_lt_f32_e64 vcc, |v71|, s25
	s_nop 1
	v_cndmask_b32_e32 v47, v71, v73, vcc
	v_add_f32_e32 v71, 1.0, v70
	v_rcp_f32_e32 v78, v71
	v_cndmask_b32_e64 v71, 0, v53, s[10:11]
	v_sub_f32_e32 v47, v47, v71
	v_add_f32_e32 v99, v47, v98
	v_fma_f32 v47, v20, v78, v110
	v_cmp_gt_f32_e32 vcc, s23, v47
	s_nop 1
	v_cndmask_b32_e64 v71, 0, 32, vcc
	v_ldexp_f32 v47, v47, v71
	v_exp_f32_e32 v71, v46
	v_log_f32_e32 v47, v47
	v_add_f32_e32 v73, 1.0, v71
	v_rcp_f32_e32 v79, v73
	v_mul_f32_e32 v46, 0x3f317217, v47
	v_fma_f32 v46, v47, s24, -v46
	v_fmac_f32_e32 v46, 0x3377d1cf, v47
	v_fmac_f32_e32 v46, 0x3f317217, v47
	v_cmp_lt_f32_e64 s[10:11], |v47|, s25
	v_fma_f32 v72, v20, v79, v110
	s_nop 0
	v_cndmask_b32_e64 v46, v47, v46, s[10:11]
	v_cmp_gt_f32_e64 s[10:11], s23, v72
	s_nop 1
	v_cndmask_b32_e64 v47, 0, 32, s[10:11]
	v_ldexp_f32 v47, v72, v47
	v_log_f32_e32 v47, v47
	v_cndmask_b32_e32 v72, 0, v53, vcc
	v_sub_f32_e32 v46, v46, v72
	v_add_f32_e32 v100, v46, v99
	v_mul_f32_e32 v46, 0x3f317217, v47
	v_fma_f32 v46, v47, s24, -v46
	v_fmac_f32_e32 v46, 0x3377d1cf, v47
	v_fmac_f32_e32 v46, 0x3f317217, v47
	v_cmp_lt_f32_e64 vcc, |v47|, s25
	s_nop 1
	v_cndmask_b32_e32 v46, v47, v46, vcc
	v_cndmask_b32_e64 v47, 0, v53, s[10:11]
	v_sub_f32_e32 v46, v46, v47
	v_add_f32_e32 v101, v46, v100
	ds_write_b32 v49, v101
	s_waitcnt lgkmcnt(0)
	s_barrier
; #define LAS __attribute__((address_space(3)))
; __device__ __forceinline__ unsigned pk2(float lo, float hi) { return cvtpk_(lo, hi); }
; __device__ __forceinline__ void hgrn_passA_units(LAS unsigned char* lds, const bf16_t* HZ, const bf16_t* HVT, const float* LB, bf16_t* U, float* DC, int bid, int G, int tid) {
;     ...
;         const float t0 = TOT[k], t1 = TOT[128 + k], t2 = TOT[256 + k], t3 = TOT[384 + k];
;         const float rI = (I > 0 ? t0 : 0.f) + (I > 1 ? t1 : 0.f) + (I > 2 ? t2 : 0.f);
;         const float blast = (t0 + t1) + (t2 + t3);
;         unsigned pw[8];
; #pragma unroll
;         for (int i = 0; i < 8; ++i) pw[i] = pk2(kk[2 * i] * __expf(blast - rI - cs[2 * i]), kk[2 * i + 1] * __expf(blast - rI - cs[2 * i + 1]));
;         LAS u32x4* kd = (LAS u32x4*)(KT + k * 72 + 16 * I);
;         kd[0] = (u32x4){pw[0], pw[1], pw[2], pw[3]}; kd[1] = (u32x4){pw[4], pw[5], pw[6], pw[7]};
;         if (I == 0) DC[(size_t)ch * 128 + k] = __expf(blast);
	ds_read2st64_b32 v[46:47], v50 offset1:2
	ds_read2st64_b32 v[72:73], v50 offset0:4 offset1:6
	s_and_b32 s10, s20, 0xfffffc00
	s_or_b32 s10, s28, s10
	s_or_b32 s10, s10, s21
	s_waitcnt lgkmcnt(1)
	v_cndmask_b32_e64 v81, 0, v46, s[0:1]
	v_cndmask_b32_e64 v83, 0, v47, s[8:9]
	v_mov_b32_e32 v80, v46
	v_mov_b32_e32 v82, v47
	s_waitcnt lgkmcnt(0)
	v_cndmask_b32_e64 v85, 0, v72, s[4:5]
	v_add_f32_e32 v84, v72, v73
	v_pk_add_f32 v[46:47], v[80:81], v[82:83]
	s_ashr_i32 s11, s10, 31
	v_pk_add_f32 v[46:47], v[46:47], v[84:85]
	s_nop 0
	v_sub_f32_e32 v47, v46, v47
	v_sub_f32_e32 v72, v47, v86
	v_sub_f32_e32 v73, v47, v87
	v_mul_f32_e32 v72, 0x3fb8aa3b, v72
	v_mul_f32_e32 v73, 0x3fb8aa3b, v73
	v_exp_f32_e32 v72, v72
	v_exp_f32_e32 v73, v73
	v_sub_f32_e32 v24, v47, v88
	v_sub_f32_e32 v25, v47, v89
	v_mul_f32_e32 v24, 0x3fb8aa3b, v24
	v_mul_f32_e32 v25, 0x3fb8aa3b, v25
	v_exp_f32_e32 v24, v24
	v_exp_f32_e32 v25, v25
	v_pk_mul_f32 v[22:23], v[22:23], v[72:73]
	v_pk_mul_f32 v[24:25], v[26:27], v[24:25]
	v_cvt_pk_bf16_f32 v22, v22, v23
	v_sub_f32_e32 v23, v47, v90
	v_mul_f32_e32 v23, 0x3fb8aa3b, v23
	v_exp_f32_e32 v26, v23
	v_sub_f32_e32 v23, v47, v91
	v_mul_f32_e32 v23, 0x3fb8aa3b, v23
	v_exp_f32_e32 v27, v23
	v_cvt_pk_bf16_f32 v23, v24, v25
	v_pk_mul_f32 v[24:25], v[30:31], v[20:21] op_sel_hi:[1,0]
	v_pk_mul_f32 v[30:31], v[42:43], v[20:21] op_sel_hi:[1,0]
	v_pk_mul_f32 v[24:25], v[32:33], v[24:25]
	v_pk_mul_f32 v[30:31], v[44:45], v[30:31]
	v_pk_mul_f32 v[24:25], v[24:25], v[26:27]
	v_sub_f32_e32 v26, v47, v92
	v_sub_f32_e32 v27, v47, v93
	v_mul_f32_e32 v26, 0x3fb8aa3b, v26
	v_mul_f32_e32 v27, 0x3fb8aa3b, v27
	v_exp_f32_e32 v26, v26
	v_exp_f32_e32 v27, v27
	v_cvt_pk_bf16_f32 v24, v24, v25
	v_sub_f32_e32 v25, v47, v94
	v_mul_f32_e32 v25, 0x3fb8aa3b, v25
	v_pk_mul_f32 v[26:27], v[28:29], v[26:27]
	v_exp_f32_e32 v28, v25
	v_sub_f32_e32 v25, v47, v95
	v_mul_f32_e32 v25, 0x3fb8aa3b, v25
	v_exp_f32_e32 v29, v25
	v_cvt_pk_bf16_f32 v25, v26, v27
	v_pk_mul_f32 v[26:27], v[38:39], v[20:21] op_sel_hi:[1,0]
	v_pk_mul_f32 v[32:33], v[20:21], v[70:71] op_sel_hi:[0,1]
	v_pk_mul_f32 v[26:27], v[40:41], v[26:27]
	v_pk_mul_f32 v[32:33], v[32:33], v[78:79]
	v_pk_mul_f32 v[26:27], v[26:27], v[28:29]
	v_sub_f32_e32 v28, v47, v96
	v_sub_f32_e32 v29, v47, v97
	v_mul_f32_e32 v28, 0x3fb8aa3b, v28
	v_mul_f32_e32 v29, 0x3fb8aa3b, v29
	v_exp_f32_e32 v28, v28
	v_exp_f32_e32 v29, v29
	v_cvt_pk_bf16_f32 v26, v26, v27
	v_sub_f32_e32 v27, v47, v98
	v_mul_f32_e32 v27, 0x3fb8aa3b, v27
	v_pk_mul_f32 v[28:29], v[30:31], v[28:29]
	v_exp_f32_e32 v30, v27
	v_sub_f32_e32 v27, v47, v99
	v_mul_f32_e32 v27, 0x3fb8aa3b, v27
	v_exp_f32_e32 v31, v27
	v_cvt_pk_bf16_f32 v27, v28, v29
	v_pk_mul_f32 v[28:29], v[74:75], v[20:21] op_sel_hi:[1,0]
	s_nop 0
	v_pk_mul_f32 v[28:29], v[28:29], v[76:77]
	s_nop 0
	v_pk_mul_f32 v[28:29], v[28:29], v[30:31]
	v_sub_f32_e32 v30, v47, v100
	v_sub_f32_e32 v31, v47, v101
	v_mul_f32_e32 v30, 0x3fb8aa3b, v30
	v_mul_f32_e32 v31, 0x3fb8aa3b, v31
	v_exp_f32_e32 v30, v30
	v_exp_f32_e32 v31, v31
	v_cvt_pk_bf16_f32 v28, v28, v29
	v_pk_mul_f32 v[30:31], v[32:33], v[30:31]
	s_nop 0
	v_cvt_pk_bf16_f32 v29, v30, v31
	ds_write_b128 v17, v[22:25] offset:2048
	ds_write_b128 v17, v[26:29] offset:2064
	s_and_saveexec_b64 s[20:21], s[6:7]
	s_cbranch_execz .LBB0_230
	v_mul_f32_e32 v20, 0x3fb8aa3b, v46
	v_exp_f32_e32 v20, v20
	s_lshl_b64 s[28:29], s[10:11], 9
	v_lshl_add_u64 v[22:23], v[14:15], 0, s[28:29]
	global_store_dword v[22:23], v20, off
	s_branch .LBB0_230

; template <bool XIB, bool XOB> __device__ __forceinline__ void rowpass(const bf16_t* Y, const float* part, const void* Xin, void* Xout, const float* g_post, const float* g_pre, bf16_t* Hout, int gw, int ngw, int lane_) {
;     int lane = lane_; asm volatile("" : "+v"(lane));
;     f32x4 gp[8];
; #pragma unroll
;     for (int j = 0; j < 8; ++j) gp[j] = ((const f32x4*)g_post)[lane + 64 * j];
;     u32x2 ny[8]; f32x4 nxf[8]; u32x2 nxb[8]; float np = 0.f;
;     ...
;     int row = gw;
;     if (row < T) RP_LOAD(row);
;     for (; row < T; row += ngw) {
;         u32x2 cy[8]; f32x4 cx[8]; float p = np;
; #pragma unroll
;         for (int j = 0; j < 8; ++j) { cy[j] = ny[j]; if (XIB) cx[j] = (f32x4){bflo(nxb[j].x), bfhi(nxb[j].x), bflo(nxb[j].y), bfhi(nxb[j].y)}; else cx[j] = nxf[j]; }
;         if (row + ngw < T) RP_LOAD(row + ngw);
.LBB0_696:
	s_or_b64 exec, exec, s[4:5]
	s_waitcnt lgkmcnt(0)
	s_barrier
	v_mbcnt_lo_u32_b32 v0, -1, 0
	v_mbcnt_hi_u32_b32 v0, -1, v0
	s_nop 0
	v_add_u32_e32 v0, s84, v0
	s_nop 0
	v_readfirstlane_b32 s2, v0
	s_ashr_i32 s2, s2, 6
	s_add_i32 s4, s2, s92
	s_add_i32 s2, 0, 0x23c40
	v_and_b32_e32 v32, 63, v0
	v_mov_b32_e32 v0, s2
	s_add_i32 s2, 0, 0x23ce0
	v_mov_b32_e32 v1, s2
	s_add_i32 s2, 0, 0x23c98
	ds_read_b64 v[4:5], v0
	ds_read_b64 v[6:7], v1
	v_mov_b32_e32 v0, s2
	ds_read2_b64 v[0:3], v0 offset1:1
	s_cmpk_lt_i32 s4, 0x4000
	s_waitcnt lgkmcnt(2)
	v_readfirstlane_b32 s2, v5
	v_readfirstlane_b32 s3, v4
	s_waitcnt lgkmcnt(1)
	v_readfirstlane_b32 s12, v7
	v_readfirstlane_b32 s13, v6
	s_waitcnt lgkmcnt(0)
	v_readfirstlane_b32 s9, v1
	v_readfirstlane_b32 s8, v0
	v_readfirstlane_b32 s7, v3
	v_readfirstlane_b32 s6, v2
	s_cbranch_scc0 .LBB0_701
	v_ashrrev_i32_e32 v33, 31, v32
	v_lshlrev_b64 v[34:35], 4, v[32:33]
	v_lshl_add_u64 v[16:17], s[8:9], 0, v[34:35]
	v_add_co_u32_e32 v36, vcc, 0x1000, v16
	s_ashr_i32 s5, s4, 31
	s_nop 0
	v_addc_co_u32_e32 v37, vcc, 0, v17, vcc
	s_lshl_b64 s[8:9], s[4:5], 7
	global_load_dwordx4 v[0:3], v[16:17], off
	global_load_dwordx4 v[4:7], v[16:17], off offset:1024
	global_load_dwordx4 v[8:11], v[16:17], off offset:2048
	global_load_dwordx4 v[12:15], v[16:17], off offset:3072
	s_nop 0
	global_load_dwordx4 v[16:19], v[36:37], off
	global_load_dwordx4 v[20:23], v[36:37], off offset:1024
	global_load_dwordx4 v[24:27], v[36:37], off offset:2048
	global_load_dwordx4 v[28:31], v[36:37], off offset:3072
	v_and_b32_e32 v36, 31, v32
	s_add_u32 s8, s10, s8
	s_addc_u32 s9, s11, s9
	v_lshlrev_b32_e32 v36, 2, v36
	s_lshl_b64 s[14:15], s[4:5], 12
	global_load_dword v142, v36, s[8:9]
	s_add_u32 s8, s56, s14
	s_addc_u32 s9, s57, s15
	v_lshlrev_b64 v[96:97], 3, v[32:33]
	v_lshl_add_u64 v[32:33], s[8:9], 0, v[96:97]
	s_lshl_b64 s[8:9], s[4:5], 13
	s_add_u32 s8, s3, s8
	s_addc_u32 s9, s2, s9
	s_movk_i32 s16, 0x1000
	v_lshl_add_u64 v[38:39], s[8:9], 0, v[34:35]
	global_load_dwordx4 v[88:91], v[38:39], off
	global_load_dwordx4 v[92:95], v[38:39], off offset:1024
	global_load_dwordx2 v[146:147], v[32:33], off
	global_load_dwordx2 v[140:141], v[32:33], off offset:512
	global_load_dwordx2 v[138:139], v[32:33], off offset:1024
	global_load_dwordx2 v[136:137], v[32:33], off offset:1536
	global_load_dwordx4 v[84:87], v[38:39], off offset:2048
	global_load_dwordx4 v[80:83], v[38:39], off offset:3072
	v_add_co_u32_e32 v38, vcc, s16, v38
	v_lshl_add_u64 v[98:99], s[6:7], 0, v[34:35]
	s_nop 0
	v_addc_co_u32_e32 v39, vcc, 0, v39, vcc
	global_load_dwordx4 v[76:79], v[38:39], off
	global_load_dwordx4 v[72:75], v[38:39], off offset:1024
	global_load_dwordx4 v[68:71], v[38:39], off offset:2048
	global_load_dwordx4 v[64:67], v[38:39], off offset:3072
	global_load_dwordx2 v[134:135], v[32:33], off offset:2048
	global_load_dwordx2 v[132:133], v[32:33], off offset:2560
	global_load_dwordx2 v[130:131], v[32:33], off offset:3072
	global_load_dwordx2 v[128:129], v[32:33], off offset:3584
	v_mbcnt_hi_u32_b32 v32, -1, v254
	v_and_b32_e32 v33, 64, v32
	v_add_u32_e32 v33, 64, v33
	v_xor_b32_e32 v38, 1, v32
	v_cmp_lt_i32_e32 vcc, v38, v33
	s_mov_b64 s[6:7], 0x1400
	v_lshl_add_u64 v[102:103], v[98:99], 0, s[6:7]
	v_cndmask_b32_e32 v38, v32, v38, vcc
	v_lshlrev_b32_e32 v148, 2, v38
	v_xor_b32_e32 v38, 2, v32
	v_cmp_lt_i32_e32 vcc, v38, v33
	s_mov_b64 s[6:7], 0x1800
	v_lshl_add_u64 v[104:105], v[98:99], 0, s[6:7]
	v_cndmask_b32_e32 v38, v32, v38, vcc
	v_lshlrev_b32_e32 v149, 2, v38
	v_xor_b32_e32 v38, 4, v32
	s_mov_b64 s[6:7], 0x1c00
	v_cmp_lt_i32_e32 vcc, v38, v33
	v_lshl_add_u64 v[106:107], v[98:99], 0, s[6:7]
	s_add_u32 s6, s13, s14
	v_cndmask_b32_e32 v38, v32, v38, vcc
	s_addc_u32 s7, s12, s15
	s_ashr_i32 s51, s50, 31
	v_lshlrev_b32_e32 v150, 2, v38
	v_xor_b32_e32 v38, 8, v32
	s_lshl_b64 s[8:9], s[50:51], 12
	v_cmp_lt_i32_e32 vcc, v38, v33
	s_add_u32 s12, s52, s14
	s_addc_u32 s13, s53, s15
	v_cndmask_b32_e32 v38, v32, v38, vcc
	s_add_i32 s18, s4, s50
	v_lshlrev_b32_e32 v151, 2, v38
	v_xor_b32_e32 v38, 16, v32
	s_ashr_i32 s19, s18, 31
	v_cmp_lt_i32_e32 vcc, v38, v33
	s_lshl_b64 s[14:15], s[18:19], 12
	s_add_u32 s14, s52, s14
	v_cndmask_b32_e32 v38, v32, v38, vcc
	v_lshlrev_b32_e32 v152, 2, v38
	v_xor_b32_e32 v38, 32, v32
	s_addc_u32 s15, s53, s15
	s_lshl_b64 s[20:21], s[18:19], 13
	v_cmp_lt_i32_e32 vcc, v38, v33
	s_add_u32 s20, s3, s20
	s_addc_u32 s21, s2, s21
	v_cndmask_b32_e32 v32, v32, v38, vcc
	v_lshlrev_b32_e32 v153, 2, v32
	s_mov_b64 s[16:17], 0x1000
	v_lshl_add_u64 v[32:33], s[20:21], 0, v[34:35]
	v_lshl_add_u64 v[100:101], v[98:99], 0, s[16:17]
	v_lshl_add_u64 v[108:109], v[32:33], 0, s[16:17]
	s_lshl_b64 s[16:17], s[50:51], 13
	s_lshl_b64 s[2:3], s[18:19], 7
	s_add_u32 s2, s52, s2
	v_mov_b32_e32 v37, 0
	s_addc_u32 s3, s53, s3
	v_lshl_add_u64 v[32:33], s[2:3], 0, v[36:37]
	s_mov_b64 s[2:3], 0xa600000
	v_lshl_add_u64 v[110:111], v[32:33], 0, s[2:3]
	global_load_dwordx4 v[200:203], v[98:99], off
	global_load_dwordx4 v[204:207], v[98:99], off offset:1024
	global_load_dwordx4 v[208:211], v[98:99], off offset:2048
	global_load_dwordx4 v[212:215], v[98:99], off offset:3072
	global_load_dwordx4 v[216:219], v[100:101], off
	global_load_dwordx4 v[220:223], v[102:103], off
	global_load_dwordx4 v[224:227], v[104:105], off
	global_load_dwordx4 v[228:231], v[106:107], off
	s_lshl_b64 s[18:19], s[50:51], 7
	v_mov_b32_e32 v154, 0x358637bd
	s_mov_b32 s2, 0x800000
	s_mov_b32 s3, 0x5c00000
	s_waitcnt vmcnt(16)
	v_mov_b32_e32 v155, v142
	s_waitcnt vmcnt(15)
	v_mov_b64_e32 v[32:33], v[88:89]
	s_waitcnt vmcnt(14)
	v_mov_b64_e32 v[36:37], v[92:93]
	v_mov_b64_e32 v[34:35], v[90:91]
	v_mov_b64_e32 v[38:39], v[94:95]
	s_waitcnt vmcnt(13)
	v_mov_b64_e32 v[112:113], v[146:147]
	s_waitcnt vmcnt(12)
	v_mov_b64_e32 v[114:115], v[140:141]
	s_waitcnt vmcnt(9)
	v_mov_b64_e32 v[40:41], v[84:85]
	s_waitcnt vmcnt(8)
	v_mov_b64_e32 v[44:45], v[80:81]
	s_waitcnt vmcnt(7)
	v_mov_b64_e32 v[48:49], v[76:77]
	s_waitcnt vmcnt(6)
	v_mov_b64_e32 v[52:53], v[72:73]
	s_waitcnt vmcnt(5)
	v_mov_b64_e32 v[56:57], v[68:69]
	s_waitcnt vmcnt(4)
	v_mov_b64_e32 v[60:61], v[64:65]
	v_mov_b64_e32 v[42:43], v[86:87]
	v_mov_b64_e32 v[46:47], v[82:83]
	v_mov_b64_e32 v[50:51], v[78:79]
	v_mov_b64_e32 v[54:55], v[74:75]
	v_mov_b64_e32 v[58:59], v[70:71]
	v_mov_b64_e32 v[62:63], v[66:67]
	v_mov_b64_e32 v[116:117], v[138:139]
	v_mov_b64_e32 v[118:119], v[136:137]
	s_waitcnt vmcnt(3)
	v_mov_b64_e32 v[120:121], v[134:135]
	s_waitcnt vmcnt(2)
	v_mov_b64_e32 v[122:123], v[132:133]
	s_waitcnt vmcnt(1)
	v_mov_b64_e32 v[124:125], v[130:131]
	s_waitcnt vmcnt(0)
	v_mov_b64_e32 v[126:127], v[128:129]
	s_branch .LBB0_699
; __device__ __forceinline__ unsigned pk2(float lo, float hi) { return cvtpk_(lo, hi); }
; template <bool XIB, bool XOB> __device__ __forceinline__ void rowpass(const bf16_t* Y, const float* part, const void* Xin, void* Xout, const float* g_post, const float* g_pre, bf16_t* Hout, int gw, int ngw, int lane_) {
;     ...
;     for (; row < T; row += ngw) {
;         u32x2 cy[8]; f32x4 cx[8]; float p = np;
; #pragma unroll
;         for (int j = 0; j < 8; ++j) { cy[j] = ny[j]; if (XIB) cx[j] = (f32x4){bflo(nxb[j].x), bfhi(nxb[j].x), bflo(nxb[j].y), bfhi(nxb[j].y)}; else cx[j] = nxf[j]; }
;         if (row + ngw < T) RP_LOAD(row + ngw);
; #pragma unroll
;         for (int o = 1; o < 32; o <<= 1) p += __shfl_xor(p, o);
;         const float rstd = rsqrtf(p * (1.0f / DM) + RMS_EPS);
;         f32x4* of = (f32x4*)((float*)Xout + (size_t)row * DM) + lane; u32x2* ob = (u32x2*)((bf16_t*)Xout + (size_t)row * DM) + lane;
;         f32x4 v[8]; float s = 0.f;
; #pragma unroll
;         for (int j = 0; j < 8; ++j) {
;             const f32x4 y = {bflo(cy[j].x), bfhi(cy[j].x), bflo(cy[j].y), bfhi(cy[j].y)};
;             v[j] = cx[j] + y * rstd * gp[j];
;             if (XOB) { u32x2 o2; o2.x = pk2(v[j][0], v[j][1]); o2.y = pk2(v[j][2], v[j][3]); ob[64 * j] = o2; } else of[64 * j] = v[j];
;             s += (v[j][0] * v[j][0] + v[j][1] * v[j][1]) + (v[j][2] * v[j][2] + v[j][3] * v[j][3]);
.LBB0_698:
	ds_bpermute_b32 v143, v148, v142
	v_lshlrev_b32_e32 v144, 16, v147
	v_and_b32_e32 v145, 0xffff0000, v147
	v_and_b32_e32 v147, 0xffff0000, v140
	v_lshl_add_u64 v[156:157], s[6:7], 0, v[96:97]
	s_waitcnt lgkmcnt(0)
	v_add_f32_e32 v142, v142, v143
	ds_bpermute_b32 v143, v149, v142
	s_add_u32 s6, s6, s8
	s_addc_u32 s7, s7, s9
	v_lshl_add_u64 v[108:109], v[108:109], 0, s[16:17]
	v_lshl_add_u64 v[110:111], v[110:111], 0, s[18:19]
	s_waitcnt lgkmcnt(0)
	v_add_f32_e32 v142, v142, v143
	ds_bpermute_b32 v143, v150, v142
	s_waitcnt lgkmcnt(0)
	v_add_f32_e32 v158, v142, v143
	ds_bpermute_b32 v159, v151, v158
	v_lshlrev_b32_e32 v142, 16, v146
	v_and_b32_e32 v143, 0xffff0000, v146
	v_lshlrev_b32_e32 v146, 16, v140
	v_lshlrev_b32_e32 v140, 16, v141
	s_waitcnt lgkmcnt(0)
	v_add_f32_e32 v158, v158, v159
	ds_bpermute_b32 v159, v152, v158
	v_and_b32_e32 v141, 0xffff0000, v141
	s_waitcnt lgkmcnt(0)
	v_add_f32_e32 v158, v158, v159
	v_fmamk_f32 v158, v158, 0x3a000000, v154
	v_mul_f32_e32 v159, 0x4b800000, v158
	v_cmp_gt_f32_e32 vcc, s2, v158
	s_nop 1
	v_cndmask_b32_e32 v158, v158, v159, vcc
	v_rsq_f32_e32 v160, v158
	v_lshlrev_b32_e32 v158, 16, v138
	v_and_b32_e32 v159, 0xffff0000, v138
	v_lshlrev_b32_e32 v138, 16, v139
	v_mul_f32_e32 v161, 0x45800000, v160
	v_cndmask_b32_e32 v160, v160, v161, vcc
	v_pk_mul_f32 v[142:143], v[160:161], v[142:143] op_sel_hi:[0,1]
	v_pk_mul_f32 v[144:145], v[160:161], v[144:145] op_sel_hi:[0,1]
	v_pk_mul_f32 v[162:163], v[160:161], v[146:147] op_sel_hi:[0,1]
	v_pk_mul_f32 v[164:165], v[160:161], v[140:141] op_sel_hi:[0,1]
	v_pk_fma_f32 v[140:141], v[2:3], v[144:145], v[90:91]
	v_pk_fma_f32 v[146:147], v[0:1], v[142:143], v[88:89]
	v_pk_fma_f32 v[88:89], v[6:7], v[164:165], v[94:95]
	v_pk_fma_f32 v[90:91], v[4:5], v[162:163], v[92:93]
	v_cvt_pk_bf16_f32 v92, v146, v147
	v_cvt_pk_bf16_f32 v93, v140, v141
	v_cvt_pk_bf16_f32 v94, v90, v91
	v_cvt_pk_bf16_f32 v95, v88, v89
	v_and_b32_e32 v139, 0xffff0000, v139
	global_store_dwordx2 v[156:157], v[92:93], off
	global_store_dwordx2 v[156:157], v[94:95], off offset:512
	v_pk_mul_f32 v[92:93], v[160:161], v[158:159] op_sel_hi:[0,1]
	v_pk_mul_f32 v[94:95], v[160:161], v[138:139] op_sel_hi:[0,1]
	v_pk_fma_f32 v[86:87], v[10:11], v[94:95], v[86:87]
	v_pk_fma_f32 v[84:85], v[8:9], v[92:93], v[84:85]
	v_cvt_pk_bf16_f32 v93, v86, v87
	v_cvt_pk_bf16_f32 v92, v84, v85
	global_store_dwordx2 v[156:157], v[92:93], off offset:1024
	v_lshlrev_b32_e32 v92, 16, v136
	v_and_b32_e32 v93, 0xffff0000, v136
	v_lshlrev_b32_e32 v94, 16, v137
	v_and_b32_e32 v95, 0xffff0000, v137
	v_pk_mul_f32 v[92:93], v[160:161], v[92:93] op_sel_hi:[0,1]
	v_pk_mul_f32 v[94:95], v[160:161], v[94:95] op_sel_hi:[0,1]
	v_pk_fma_f32 v[82:83], v[14:15], v[94:95], v[82:83]
	v_pk_fma_f32 v[80:81], v[12:13], v[92:93], v[80:81]
	v_cvt_pk_bf16_f32 v93, v82, v83
	v_cvt_pk_bf16_f32 v92, v80, v81
	global_store_dwordx2 v[156:157], v[92:93], off offset:1536
	v_lshlrev_b32_e32 v92, 16, v134
	v_and_b32_e32 v93, 0xffff0000, v134
	v_lshlrev_b32_e32 v94, 16, v135
	v_and_b32_e32 v95, 0xffff0000, v135
	v_pk_mul_f32 v[92:93], v[160:161], v[92:93] op_sel_hi:[0,1]
	v_pk_mul_f32 v[94:95], v[160:161], v[94:95] op_sel_hi:[0,1]
	v_pk_fma_f32 v[78:79], v[18:19], v[94:95], v[78:79]
	v_pk_fma_f32 v[76:77], v[16:17], v[92:93], v[76:77]
	v_cvt_pk_bf16_f32 v93, v78, v79
	v_cvt_pk_bf16_f32 v92, v76, v77
	global_store_dwordx2 v[156:157], v[92:93], off offset:2048
	v_lshlrev_b32_e32 v92, 16, v132
	v_and_b32_e32 v93, 0xffff0000, v132
	v_lshlrev_b32_e32 v94, 16, v133
	v_and_b32_e32 v95, 0xffff0000, v133
	v_pk_mul_f32 v[92:93], v[160:161], v[92:93] op_sel_hi:[0,1]
	v_pk_mul_f32 v[94:95], v[160:161], v[94:95] op_sel_hi:[0,1]
	v_pk_fma_f32 v[74:75], v[22:23], v[94:95], v[74:75]
	v_pk_fma_f32 v[72:73], v[20:21], v[92:93], v[72:73]
	v_cvt_pk_bf16_f32 v93, v74, v75
	v_cvt_pk_bf16_f32 v92, v72, v73
	global_store_dwordx2 v[156:157], v[92:93], off offset:2560
	v_lshlrev_b32_e32 v92, 16, v130
	v_and_b32_e32 v93, 0xffff0000, v130
	v_lshlrev_b32_e32 v94, 16, v131
	v_and_b32_e32 v95, 0xffff0000, v131
	v_pk_mul_f32 v[92:93], v[160:161], v[92:93] op_sel_hi:[0,1]
	v_pk_mul_f32 v[94:95], v[160:161], v[94:95] op_sel_hi:[0,1]
	v_pk_fma_f32 v[70:71], v[26:27], v[94:95], v[70:71]
	v_pk_fma_f32 v[68:69], v[24:25], v[92:93], v[68:69]
	v_cvt_pk_bf16_f32 v93, v70, v71
	v_cvt_pk_bf16_f32 v92, v68, v69
	global_store_dwordx2 v[156:157], v[92:93], off offset:3072
	v_lshlrev_b32_e32 v92, 16, v128
	v_and_b32_e32 v93, 0xffff0000, v128
	v_lshlrev_b32_e32 v94, 16, v129
	v_and_b32_e32 v95, 0xffff0000, v129
	v_pk_mul_f32 v[92:93], v[160:161], v[92:93] op_sel_hi:[0,1]
	v_pk_mul_f32 v[94:95], v[160:161], v[94:95] op_sel_hi:[0,1]
	v_pk_fma_f32 v[142:143], v[30:31], v[94:95], v[66:67]
	v_pk_fma_f32 v[144:145], v[28:29], v[92:93], v[64:65]
	v_cvt_pk_bf16_f32 v65, v142, v143
	v_cvt_pk_bf16_f32 v64, v144, v145
	v_mov_b32_e32 v66, v147
	v_mov_b32_e32 v67, v91
	global_store_dwordx2 v[156:157], v[64:65], off offset:3584
	v_mov_b32_e32 v64, v146
	v_mov_b32_e32 v65, v90
	v_pk_mul_f32 v[66:67], v[66:67], v[66:67]
	v_mov_b32_e32 v92, v140
	v_mov_b32_e32 v93, v88
	v_pk_fma_f32 v[64:65], v[64:65], v[64:65], v[66:67]
	v_mov_b32_e32 v66, v141
	v_mov_b32_e32 v67, v89
	v_pk_mul_f32 v[92:93], v[92:93], v[92:93]
	v_pk_fma_f32 v[66:67], v[66:67], v[66:67], v[92:93]
	v_pk_add_f32 v[64:65], v[64:65], v[66:67]
	v_pk_mul_f32 v[66:67], v[86:87], v[86:87]
	v_pk_add_f32 v[92:93], v[64:65], v[64:65] op_sel_hi:[0,1]
	v_pk_mul_f32 v[64:65], v[84:85], v[84:85]
	v_mov_b32_e32 v95, v67
	v_mov_b32_e32 v94, v64
	v_pk_mov_b32 v[64:65], v[64:65], v[66:67] op_sel:[1,0]
	v_mul_f32_e32 v92, v80, v80
	v_pk_add_f32 v[64:65], v[94:95], v[64:65]
; __device__ __forceinline__ unsigned pk2(float lo, float hi) { return cvtpk_(lo, hi); }
; template <bool XIB, bool XOB> __device__ __forceinline__ void rowpass(const bf16_t* Y, const float* part, const void* Xin, void* Xout, const float* g_post, const float* g_pre, bf16_t* Hout, int gw, int ngw, int lane_) {
;     ...
;             s += (v[j][0] * v[j][0] + v[j][1] * v[j][1]) + (v[j][2] * v[j][2] + v[j][3] * v[j][3]);
;         }
;         if (Hout) {
;             const float r2 = rsqrtf(wave_sum(s) * (1.0f / DM) + RMS_EPS);
;             const f32x4* gq = (const f32x4*)g_pre + lane; u32x2* o8 = (u32x2*)(Hout + (size_t)row * DM) + lane;
; #pragma unroll
;             for (int j = 0; j < 8; ++j) { const f32x4 g = gq[64 * j]; u32x2 w; w.x = pk2(v[j][0] * r2 * g[0], v[j][1] * r2 * g[1]); w.y = pk2(v[j][2] * r2 * g[2], v[j][3] * r2 * g[3]); o8[64 * j] = w; }
;         }
	v_pk_fma_f32 v[128:129], v[80:81], v[80:81], v[92:93] op_sel_hi:[1,1,0]
	v_pk_add_f32 v[94:95], v[64:65], v[64:65] op_sel_hi:[0,1]
	v_mul_f32_e32 v92, v82, v82
	v_pk_fma_f32 v[130:131], v[82:83], v[82:83], v[92:93] op_sel_hi:[1,1,0]
	v_mul_f32_e32 v128, v76, v76
	v_mul_f32_e32 v130, v77, v77
	v_mul_f32_e32 v94, v79, v79
	v_mul_f32_e32 v92, v78, v78
	v_pk_add_f32 v[128:129], v[128:129], v[130:131]
	v_pk_add_f32 v[92:93], v[94:95], v[92:93]
	v_pk_mul_f32 v[94:95], v[72:73], v[72:73]
	v_pk_add_f32 v[92:93], v[128:129], v[92:93]
	v_pk_mul_f32 v[128:129], v[74:75], v[74:75]
	v_pk_add_f32 v[92:93], v[92:93], v[92:93] op_sel_hi:[0,1]
	v_mov_b32_e32 v130, v94
	v_mov_b32_e32 v131, v129
	v_pk_mov_b32 v[94:95], v[94:95], v[128:129] op_sel:[1,0]
	v_mul_f32_e32 v92, v68, v68
	v_pk_add_f32 v[94:95], v[130:131], v[94:95]
	v_pk_fma_f32 v[128:129], v[68:69], v[68:69], v[92:93] op_sel_hi:[1,1,0]
	v_mul_f32_e32 v92, v70, v70
	v_pk_add_f32 v[94:95], v[94:95], v[94:95] op_sel_hi:[0,1]
	v_pk_fma_f32 v[130:131], v[70:71], v[70:71], v[92:93] op_sel_hi:[1,1,0]
	v_mul_f32_e32 v128, v144, v144
	v_mul_f32_e32 v130, v145, v145
	v_mul_f32_e32 v94, v143, v143
	v_mul_f32_e32 v92, v142, v142
	v_pk_add_f32 v[128:129], v[128:129], v[130:131]
	v_pk_add_f32 v[92:93], v[94:95], v[92:93]
	v_pk_add_f32 v[92:93], v[128:129], v[92:93]
	v_add_f32_e32 v92, v92, v93
	ds_bpermute_b32 v93, v148, v92
	s_waitcnt lgkmcnt(0)
	v_add_f32_e32 v92, v92, v93
	ds_bpermute_b32 v93, v149, v92
	s_waitcnt lgkmcnt(0)
	v_add_f32_e32 v92, v92, v93
	ds_bpermute_b32 v93, v150, v92
	s_waitcnt lgkmcnt(0)
	v_add_f32_e32 v92, v92, v93
	ds_bpermute_b32 v93, v151, v92
	s_waitcnt lgkmcnt(0)
	v_add_f32_e32 v92, v92, v93
	ds_bpermute_b32 v93, v152, v92
	s_waitcnt lgkmcnt(0)
	v_add_f32_e32 v92, v92, v93
	ds_bpermute_b32 v93, v153, v92
	s_waitcnt lgkmcnt(0)
	v_add_f32_e32 v92, v92, v93
	v_fmamk_f32 v92, v92, 0x3a000000, v154
	v_mul_f32_e32 v93, 0x4b800000, v92
	v_cmp_gt_f32_e32 vcc, s2, v92
	s_nop 1
	v_cndmask_b32_e32 v92, v92, v93, vcc
	v_rsq_f32_e32 v92, v92
	s_nop 0
	v_mul_f32_e32 v93, 0x45800000, v92
	v_cndmask_b32_e32 v160, v92, v93, vcc
	v_pk_mul_f32 v[94:95], v[146:147], v[160:161] op_sel_hi:[1,0]
	v_lshl_add_u64 v[92:93], s[12:13], 0, v[96:97]
	v_pk_mul_f32 v[64:65], v[200:201], v[94:95]
	v_pk_mul_f32 v[94:95], v[140:141], v[160:161] op_sel_hi:[1,0]
	v_add_co_u32_e32 v162, vcc, s3, v92
	v_pk_mul_f32 v[66:67], v[202:203], v[94:95]
	v_cvt_pk_bf16_f32 v64, v64, v65
	v_cvt_pk_bf16_f32 v65, v66, v67
	v_addc_co_u32_e32 v163, vcc, 0, v93, vcc
	global_store_dwordx2 v[162:163], v[64:65], off
	v_pk_mul_f32 v[90:91], v[90:91], v[160:161] op_sel_hi:[1,0]
	v_pk_mul_f32 v[88:89], v[88:89], v[160:161] op_sel_hi:[1,0]
	v_pk_mul_f32 v[84:85], v[84:85], v[160:161] op_sel_hi:[1,0]
	v_pk_mul_f32 v[86:87], v[86:87], v[160:161] op_sel_hi:[1,0]
	v_pk_mul_f32 v[80:81], v[80:81], v[160:161] op_sel_hi:[1,0]
	v_pk_mul_f32 v[82:83], v[82:83], v[160:161] op_sel_hi:[1,0]
	v_pk_mul_f32 v[76:77], v[76:77], v[160:161] op_sel_hi:[1,0]
	v_pk_mul_f32 v[78:79], v[78:79], v[160:161] op_sel_hi:[1,0]
	v_pk_mul_f32 v[72:73], v[72:73], v[160:161] op_sel_hi:[1,0]
	v_pk_mul_f32 v[74:75], v[74:75], v[160:161] op_sel_hi:[1,0]
	v_pk_mul_f32 v[68:69], v[68:69], v[160:161] op_sel_hi:[1,0]
	v_pk_mul_f32 v[70:71], v[70:71], v[160:161] op_sel_hi:[1,0]
	s_add_u32 s12, s12, s8
	s_addc_u32 s13, s13, s9
	v_pk_mul_f32 v[144:145], v[144:145], v[160:161] op_sel_hi:[1,0]
	v_pk_mul_f32 v[142:143], v[142:143], v[160:161] op_sel_hi:[1,0]
	s_add_u32 s14, s14, s8
	s_addc_u32 s15, s15, s9
	s_andn2_b64 vcc, exec, s[20:21]
	v_pk_mul_f32 v[64:65], v[204:205], v[90:91]
	v_pk_mul_f32 v[66:67], v[206:207], v[88:89]
	v_cvt_pk_bf16_f32 v64, v64, v65
	v_cvt_pk_bf16_f32 v65, v66, v67
	global_store_dwordx2 v[162:163], v[64:65], off offset:512
	v_pk_mul_f32 v[64:65], v[208:209], v[84:85]
	v_pk_mul_f32 v[66:67], v[210:211], v[86:87]
	v_cvt_pk_bf16_f32 v64, v64, v65
	v_cvt_pk_bf16_f32 v65, v66, v67
	global_store_dwordx2 v[162:163], v[64:65], off offset:1024
	v_pk_mul_f32 v[64:65], v[212:213], v[80:81]
	v_pk_mul_f32 v[66:67], v[214:215], v[82:83]
	v_cvt_pk_bf16_f32 v64, v64, v65
	v_cvt_pk_bf16_f32 v65, v66, v67
	global_store_dwordx2 v[162:163], v[64:65], off offset:1536
	v_pk_mul_f32 v[64:65], v[216:217], v[76:77]
	v_pk_mul_f32 v[66:67], v[218:219], v[78:79]
	v_cvt_pk_bf16_f32 v64, v64, v65
	v_cvt_pk_bf16_f32 v65, v66, v67
	global_store_dwordx2 v[162:163], v[64:65], off offset:2048
	v_pk_mul_f32 v[64:65], v[220:221], v[72:73]
	v_pk_mul_f32 v[66:67], v[222:223], v[74:75]
	v_cvt_pk_bf16_f32 v64, v64, v65
	v_cvt_pk_bf16_f32 v65, v66, v67
	global_store_dwordx2 v[162:163], v[64:65], off offset:2560
	v_pk_mul_f32 v[64:65], v[224:225], v[68:69]
	v_pk_mul_f32 v[66:67], v[226:227], v[70:71]
	v_cvt_pk_bf16_f32 v64, v64, v65
	v_cvt_pk_bf16_f32 v65, v66, v67
	global_store_dwordx2 v[162:163], v[64:65], off offset:3072
	v_pk_mul_f32 v[144:145], v[228:229], v[144:145]
	v_pk_mul_f32 v[142:143], v[230:231], v[142:143]
	v_cvt_pk_bf16_f32 v144, v144, v145
	v_cvt_pk_bf16_f32 v145, v142, v143
	global_store_dwordx2 v[162:163], v[144:145], off offset:3584
	s_waitcnt vmcnt(16)
	v_mov_b64_e32 v[138:139], v[116:117]
	v_mov_b64_e32 v[136:137], v[118:119]
	v_mov_b64_e32 v[134:135], v[120:121]
	v_mov_b64_e32 v[132:133], v[122:123]
	v_mov_b64_e32 v[130:131], v[124:125]
	v_mov_b64_e32 v[128:129], v[126:127]
	v_mov_b64_e32 v[94:95], v[38:39]
	v_mov_b64_e32 v[146:147], v[112:113]
	v_mov_b64_e32 v[140:141], v[114:115]
	v_mov_b64_e32 v[92:93], v[36:37]
	v_mov_b64_e32 v[90:91], v[34:35]
	v_mov_b64_e32 v[88:89], v[32:33]
	v_mov_b64_e32 v[86:87], v[42:43]
	v_mov_b64_e32 v[84:85], v[40:41]
	v_mov_b64_e32 v[82:83], v[46:47]
	v_mov_b64_e32 v[80:81], v[44:45]
	v_mov_b64_e32 v[78:79], v[50:51]
	v_mov_b64_e32 v[76:77], v[48:49]
	v_mov_b64_e32 v[74:75], v[54:55]
	v_mov_b64_e32 v[72:73], v[52:53]
	v_mov_b64_e32 v[70:71], v[58:59]
	v_mov_b64_e32 v[66:67], v[62:63]
	v_mov_b64_e32 v[68:69], v[56:57]
	v_mov_b64_e32 v[64:65], v[60:61]
	v_mov_b32_e32 v142, v155
	s_cbranch_vccz .LBB0_701

; template <bool XIB, bool XOB> __device__ __forceinline__ void rowpass(const bf16_t* Y, const float* part, const void* Xin, void* Xout, const float* g_post, const float* g_pre, bf16_t* Hout, int gw, int ngw, int lane_) {
;     int lane = lane_; asm volatile("" : "+v"(lane));
;     f32x4 gp[8];
; #pragma unroll
;     for (int j = 0; j < 8; ++j) gp[j] = ((const f32x4*)g_post)[lane + 64 * j];
;     u32x2 ny[8]; f32x4 nxf[8]; u32x2 nxb[8]; float np = 0.f;
;     ...
;     int row = gw;
;     if (row < T) RP_LOAD(row);
;     for (; row < T; row += ngw) {
;         u32x2 cy[8]; f32x4 cx[8]; float p = np;
; #pragma unroll
;         for (int j = 0; j < 8; ++j) { cy[j] = ny[j]; if (XIB) cx[j] = (f32x4){bflo(nxb[j].x), bfhi(nxb[j].x), bflo(nxb[j].y), bfhi(nxb[j].y)}; else cx[j] = nxf[j]; }
;         if (row + ngw < T) RP_LOAD(row + ngw);
.LBB0_918:
	s_or_b64 exec, exec, s[4:5]
	s_waitcnt lgkmcnt(0)
	s_barrier
	v_mbcnt_lo_u32_b32 v0, -1, 0
	v_mbcnt_hi_u32_b32 v0, -1, v0
	s_add_i32 s3, 0, 0x23ce0
	v_add_u32_e32 v0, s84, v0
	s_nop 0
	v_and_b32_e32 v32, 63, v0
	v_readfirstlane_b32 s2, v0
	v_mov_b32_e32 v0, s3
	s_add_i32 s3, 0, 0x23cb8
	ds_read_b64 v[4:5], v0
	v_mov_b32_e32 v0, s3
	ds_read2_b64 v[0:3], v0 offset1:1
	s_ashr_i32 s2, s2, 6
	s_add_i32 s4, s2, s92
	s_waitcnt lgkmcnt(1)
	v_readfirstlane_b32 s2, v5
	v_readfirstlane_b32 s3, v4
	s_waitcnt lgkmcnt(0)
	v_readfirstlane_b32 s9, v1
	v_readfirstlane_b32 s8, v0
	v_readfirstlane_b32 s7, v3
	v_readfirstlane_b32 s6, v2
	s_cmpk_lt_i32 s4, 0x4000
	s_cbranch_scc0 .LBB0_923
	v_ashrrev_i32_e32 v33, 31, v32
	v_lshlrev_b64 v[34:35], 4, v[32:33]
	s_ashr_i32 s5, s4, 31
	v_lshl_add_u64 v[16:17], s[8:9], 0, v[34:35]
	s_lshl_b64 s[8:9], s[4:5], 7
	s_add_u32 s8, s10, s8
	v_add_co_u32_e32 v36, vcc, 0x1000, v16
	s_addc_u32 s9, s11, s9
	s_lshl_b64 s[14:15], s[4:5], 12
	v_addc_co_u32_e32 v37, vcc, 0, v17, vcc
	s_add_u32 s16, s56, s14
	global_load_dwordx4 v[0:3], v[16:17], off
	global_load_dwordx4 v[4:7], v[16:17], off offset:1024
	global_load_dwordx4 v[8:11], v[16:17], off offset:2048
	global_load_dwordx4 v[12:15], v[16:17], off offset:3072
	s_nop 0
	global_load_dwordx4 v[16:19], v[36:37], off
	global_load_dwordx4 v[20:23], v[36:37], off offset:1024
	global_load_dwordx4 v[24:27], v[36:37], off offset:2048
	global_load_dwordx4 v[28:31], v[36:37], off offset:3072
	v_and_b32_e32 v36, 31, v32
	s_addc_u32 s17, s57, s15
	v_lshlrev_b64 v[32:33], 3, v[32:33]
	v_lshlrev_b32_e32 v44, 2, v36
	v_lshl_add_u64 v[36:37], s[16:17], 0, v[32:33]
	s_add_u32 s16, s3, s14
	s_addc_u32 s17, s2, s15
	v_lshl_add_u64 v[38:39], s[16:17], 0, v[32:33]
	global_load_dwordx2 v[112:113], v[38:39], off
	global_load_dwordx2 v[110:111], v[38:39], off offset:512
	global_load_dwordx2 v[104:105], v[38:39], off offset:1024
	global_load_dwordx2 v[102:103], v[38:39], off offset:1536
	global_load_dwordx2 v[100:101], v[38:39], off offset:2048
	global_load_dwordx2 v[98:99], v[38:39], off offset:2560
	global_load_dwordx2 v[96:97], v[38:39], off offset:3072
	global_load_dwordx2 v[92:93], v[38:39], off offset:3584
	global_load_dwordx2 v[94:95], v[36:37], off
	global_load_dwordx2 v[90:91], v[36:37], off offset:512
	global_load_dwordx2 v[88:89], v[36:37], off offset:1024
	global_load_dwordx2 v[86:87], v[36:37], off offset:1536
	global_load_dwordx2 v[84:85], v[36:37], off offset:2048
	global_load_dwordx2 v[82:83], v[36:37], off offset:2560
	global_load_dwordx2 v[80:81], v[36:37], off offset:3072
	global_load_dwordx2 v[78:79], v[36:37], off offset:3584
	global_load_dword v106, v44, s[8:9]
	v_mbcnt_hi_u32_b32 v36, -1, v254
	v_and_b32_e32 v37, 64, v36
	v_add_u32_e32 v37, 64, v37
	v_xor_b32_e32 v38, 1, v36
	v_cmp_lt_i32_e32 vcc, v38, v37
	v_lshl_add_u64 v[34:35], s[6:7], 0, v[34:35]
	s_mov_b64 s[6:7], 0x1000
	v_cndmask_b32_e32 v38, v36, v38, vcc
	v_lshlrev_b32_e32 v114, 2, v38
	v_xor_b32_e32 v38, 2, v36
	v_cmp_lt_i32_e32 vcc, v38, v37
	v_mov_b32_e32 v45, 0
	v_mov_b32_e32 v120, 0x358637bd
	v_cndmask_b32_e32 v38, v36, v38, vcc
	v_lshlrev_b32_e32 v115, 2, v38
	v_xor_b32_e32 v38, 4, v36
	v_cmp_lt_i32_e32 vcc, v38, v37
	s_mov_b32 s5, 0x5c00000
	s_waitcnt vmcnt(16)
	v_mov_b64_e32 v[46:47], v[112:113]
	v_cndmask_b32_e32 v38, v36, v38, vcc
	v_lshlrev_b32_e32 v116, 2, v38
	v_xor_b32_e32 v38, 8, v36
	v_cmp_lt_i32_e32 vcc, v38, v37
	s_waitcnt vmcnt(15)
	v_mov_b64_e32 v[50:51], v[110:111]
	s_waitcnt vmcnt(14)
	v_mov_b64_e32 v[52:53], v[104:105]
	v_cndmask_b32_e32 v38, v36, v38, vcc
	v_lshlrev_b32_e32 v117, 2, v38
	v_xor_b32_e32 v38, 16, v36
	v_cmp_lt_i32_e32 vcc, v38, v37
	s_waitcnt vmcnt(13)
	v_mov_b64_e32 v[56:57], v[102:103]
	s_waitcnt vmcnt(12)
	v_mov_b64_e32 v[62:63], v[100:101]
	v_cndmask_b32_e32 v38, v36, v38, vcc
	v_lshlrev_b32_e32 v118, 2, v38
	v_xor_b32_e32 v38, 32, v36
	v_cmp_lt_i32_e32 vcc, v38, v37
	s_waitcnt vmcnt(11)
	v_mov_b64_e32 v[66:67], v[98:99]
	s_waitcnt vmcnt(10)
	v_mov_b64_e32 v[68:69], v[96:97]
	v_cndmask_b32_e32 v36, v36, v38, vcc
	v_lshlrev_b32_e32 v119, 2, v36
	v_lshl_add_u64 v[36:37], v[34:35], 0, s[6:7]
	s_mov_b64 s[6:7], 0x1400
	v_lshl_add_u64 v[38:39], v[34:35], 0, s[6:7]
	s_mov_b64 s[6:7], 0x1800
	v_lshl_add_u64 v[40:41], v[34:35], 0, s[6:7]
	s_mov_b64 s[6:7], 0x1c00
	v_lshl_add_u64 v[42:43], v[34:35], 0, s[6:7]
	global_load_dwordx4 v[200:203], v[34:35], off
	global_load_dwordx4 v[204:207], v[34:35], off offset:1024
	global_load_dwordx4 v[208:211], v[34:35], off offset:2048
	global_load_dwordx4 v[212:215], v[34:35], off offset:3072
	global_load_dwordx4 v[216:219], v[36:37], off
	global_load_dwordx4 v[220:223], v[38:39], off
	global_load_dwordx4 v[224:227], v[40:41], off
	global_load_dwordx4 v[228:231], v[42:43], off
	s_add_u32 s6, s52, s14
	s_addc_u32 s7, s53, s15
	s_add_i32 s18, s4, s50
	s_ashr_i32 s51, s50, 31
	s_ashr_i32 s19, s18, 31
	s_lshl_b64 s[8:9], s[50:51], 12
	s_lshl_b64 s[16:17], s[18:19], 12
	s_add_u32 s14, s52, s16
	s_addc_u32 s15, s53, s17
	s_add_u32 s16, s3, s16
	s_addc_u32 s17, s2, s17
	s_lshl_b64 s[2:3], s[18:19], 7
	s_add_u32 s2, s52, s2
	s_addc_u32 s3, s53, s3
	v_lshl_add_u64 v[44:45], s[2:3], 0, v[44:45]
	s_mov_b64 s[2:3], 0xa600000
	v_lshl_add_u64 v[44:45], v[44:45], 0, s[2:3]
	s_lshl_b64 s[18:19], s[50:51], 7
	s_mov_b32 s2, 0x800000
	s_mov_b32 s3, 0x18e00000
	s_waitcnt vmcnt(9)
	v_mov_b64_e32 v[72:73], v[92:93]
	s_waitcnt vmcnt(8)
	v_mov_b64_e32 v[48:49], v[94:95]
	s_waitcnt vmcnt(7)
	v_mov_b64_e32 v[54:55], v[90:91]
	s_waitcnt vmcnt(6)
	v_mov_b64_e32 v[58:59], v[88:89]
	s_waitcnt vmcnt(5)
	v_mov_b64_e32 v[60:61], v[86:87]
	s_waitcnt vmcnt(4)
	v_mov_b64_e32 v[64:65], v[84:85]
	s_waitcnt vmcnt(3)
	v_mov_b64_e32 v[70:71], v[82:83]
	s_waitcnt vmcnt(2)
	v_mov_b64_e32 v[74:75], v[80:81]
	s_waitcnt vmcnt(1)
	v_mov_b64_e32 v[76:77], v[78:79]
	s_waitcnt vmcnt(0)
	v_mov_b32_e32 v121, v106
	s_branch .LBB0_921
; __device__ __forceinline__ unsigned pk2(float lo, float hi) { return cvtpk_(lo, hi); }
; template <bool XIB, bool XOB> __device__ __forceinline__ void rowpass(const bf16_t* Y, const float* part, const void* Xin, void* Xout, const float* g_post, const float* g_pre, bf16_t* Hout, int gw, int ngw, int lane_) {
;     ...
;     for (; row < T; row += ngw) {
;         u32x2 cy[8]; f32x4 cx[8]; float p = np;
; #pragma unroll
;         for (int j = 0; j < 8; ++j) { cy[j] = ny[j]; if (XIB) cx[j] = (f32x4){bflo(nxb[j].x), bfhi(nxb[j].x), bflo(nxb[j].y), bfhi(nxb[j].y)}; else cx[j] = nxf[j]; }
;         if (row + ngw < T) RP_LOAD(row + ngw);
; #pragma unroll
;         for (int o = 1; o < 32; o <<= 1) p += __shfl_xor(p, o);
;         const float rstd = rsqrtf(p * (1.0f / DM) + RMS_EPS);
;         f32x4* of = (f32x4*)((float*)Xout + (size_t)row * DM) + lane; u32x2* ob = (u32x2*)((bf16_t*)Xout + (size_t)row * DM) + lane;
;         f32x4 v[8]; float s = 0.f;
; #pragma unroll
;         for (int j = 0; j < 8; ++j) {
;             const f32x4 y = {bflo(cy[j].x), bfhi(cy[j].x), bflo(cy[j].y), bfhi(cy[j].y)};
;             v[j] = cx[j] + y * rstd * gp[j];
;             if (XOB) { u32x2 o2; o2.x = pk2(v[j][0], v[j][1]); o2.y = pk2(v[j][2], v[j][3]); ob[64 * j] = o2; } else of[64 * j] = v[j];
;             s += (v[j][0] * v[j][0] + v[j][1] * v[j][1]) + (v[j][2] * v[j][2] + v[j][3] * v[j][3]);
.LBB0_920:
	ds_bpermute_b32 v107, v114, v106
	v_and_b32_e32 v129, 0xffff0000, v101
	v_lshlrev_b32_e32 v130, 16, v98
	v_and_b32_e32 v133, 0xffff0000, v99
	v_lshlrev_b32_e32 v134, 16, v96
	s_waitcnt lgkmcnt(0)
	v_add_f32_e32 v107, v106, v107
	ds_bpermute_b32 v128, v115, v107
	v_lshlrev_b32_e32 v106, 16, v100
	v_and_b32_e32 v135, 0xffff0000, v96
	v_lshlrev_b32_e32 v136, 16, v97
	v_and_b32_e32 v137, 0xffff0000, v97
	s_waitcnt lgkmcnt(0)
	v_add_f32_e32 v131, v107, v128
	ds_bpermute_b32 v132, v116, v131
	v_and_b32_e32 v107, 0xffff0000, v100
	v_lshlrev_b32_e32 v128, 16, v101
	v_lshlrev_b32_e32 v138, 16, v92
	v_and_b32_e32 v139, 0xffff0000, v92
	s_waitcnt lgkmcnt(0)
	v_add_f32_e32 v100, v131, v132
	ds_bpermute_b32 v101, v117, v100
	v_and_b32_e32 v131, 0xffff0000, v98
	v_lshlrev_b32_e32 v132, 16, v99
	v_lshlrev_b32_e32 v108, 16, v112
	v_and_b32_e32 v109, 0xffff0000, v112
	s_waitcnt lgkmcnt(0)
	v_add_f32_e32 v98, v100, v101
	ds_bpermute_b32 v99, v118, v98
	v_lshlrev_b32_e32 v112, 16, v113
	v_and_b32_e32 v113, 0xffff0000, v113
	v_lshlrev_b32_e32 v140, 16, v93
	v_and_b32_e32 v141, 0xffff0000, v93
	s_waitcnt lgkmcnt(0)
	v_add_f32_e32 v96, v98, v99
	v_fmamk_f32 v96, v96, 0x3a000000, v120
	v_mul_f32_e32 v97, 0x4b800000, v96
	v_cmp_gt_f32_e32 vcc, s2, v96
	v_lshlrev_b32_e32 v122, 16, v110
	v_and_b32_e32 v123, 0xffff0000, v110
	v_cndmask_b32_e32 v96, v96, v97, vcc
	v_rsq_f32_e32 v96, v96
	v_and_b32_e32 v97, 0xffff0000, v94
	v_lshlrev_b32_e32 v110, 16, v111
	v_and_b32_e32 v111, 0xffff0000, v111
	v_mul_f32_e32 v92, 0x45800000, v96
	v_cndmask_b32_e32 v142, v96, v92, vcc
	v_lshlrev_b32_e32 v96, 16, v94
	v_lshlrev_b32_e32 v94, 16, v95
	v_and_b32_e32 v95, 0xffff0000, v95
	v_lshl_add_u64 v[92:93], s[6:7], 0, v[32:33]
	v_pk_mul_f32 v[96:97], v[142:143], v[96:97] op_sel_hi:[0,1]
	v_pk_mul_f32 v[94:95], v[142:143], v[94:95] op_sel_hi:[0,1]
	v_pk_fma_f32 v[94:95], v[2:3], v[94:95], v[112:113]
	v_pk_fma_f32 v[96:97], v[0:1], v[96:97], v[108:109]
	v_add_co_u32_e32 v144, vcc, s3, v92
	v_cvt_pk_bf16_f32 v98, v96, v97
	v_cvt_pk_bf16_f32 v99, v94, v95
	v_addc_co_u32_e32 v145, vcc, 0, v93, vcc
	global_store_dwordx2 v[144:145], v[98:99], off
	v_lshlrev_b32_e32 v98, 16, v90
	v_and_b32_e32 v99, 0xffff0000, v90
	v_lshlrev_b32_e32 v90, 16, v91
	v_and_b32_e32 v91, 0xffff0000, v91
	v_pk_mul_f32 v[98:99], v[142:143], v[98:99] op_sel_hi:[0,1]
	v_pk_mul_f32 v[90:91], v[142:143], v[90:91] op_sel_hi:[0,1]
	v_pk_fma_f32 v[90:91], v[6:7], v[90:91], v[110:111]
	v_pk_fma_f32 v[98:99], v[4:5], v[98:99], v[122:123]
	v_cvt_pk_bf16_f32 v101, v90, v91
	v_cvt_pk_bf16_f32 v100, v98, v99
	global_store_dwordx2 v[144:145], v[100:101], off offset:512
	v_lshlrev_b32_e32 v100, 16, v88
	v_and_b32_e32 v101, 0xffff0000, v88
	v_lshlrev_b32_e32 v88, 16, v89
	v_and_b32_e32 v89, 0xffff0000, v89
	v_lshlrev_b32_e32 v124, 16, v104
	v_and_b32_e32 v125, 0xffff0000, v104
	v_lshlrev_b32_e32 v104, 16, v105
	v_and_b32_e32 v105, 0xffff0000, v105
	v_pk_mul_f32 v[100:101], v[142:143], v[100:101] op_sel_hi:[0,1]
	v_pk_mul_f32 v[88:89], v[142:143], v[88:89] op_sel_hi:[0,1]
	v_pk_fma_f32 v[88:89], v[10:11], v[88:89], v[104:105]
	v_pk_fma_f32 v[100:101], v[8:9], v[100:101], v[124:125]
	v_cvt_pk_bf16_f32 v105, v88, v89
	v_cvt_pk_bf16_f32 v104, v100, v101
	global_store_dwordx2 v[144:145], v[104:105], off offset:1024
	v_lshlrev_b32_e32 v104, 16, v86
	v_and_b32_e32 v105, 0xffff0000, v86
	v_lshlrev_b32_e32 v86, 16, v87
	v_and_b32_e32 v87, 0xffff0000, v87
	v_lshlrev_b32_e32 v126, 16, v102
	v_and_b32_e32 v127, 0xffff0000, v102
	v_lshlrev_b32_e32 v102, 16, v103
	v_and_b32_e32 v103, 0xffff0000, v103
	v_pk_mul_f32 v[104:105], v[142:143], v[104:105] op_sel_hi:[0,1]
	v_pk_mul_f32 v[86:87], v[142:143], v[86:87] op_sel_hi:[0,1]
	v_pk_fma_f32 v[86:87], v[14:15], v[86:87], v[102:103]
	v_pk_fma_f32 v[102:103], v[12:13], v[104:105], v[126:127]
	v_cvt_pk_bf16_f32 v105, v86, v87
	v_cvt_pk_bf16_f32 v104, v102, v103
	global_store_dwordx2 v[144:145], v[104:105], off offset:1536
	v_lshlrev_b32_e32 v104, 16, v84
	v_and_b32_e32 v105, 0xffff0000, v84
	v_lshlrev_b32_e32 v84, 16, v85
	v_and_b32_e32 v85, 0xffff0000, v85
	v_pk_mul_f32 v[104:105], v[142:143], v[104:105] op_sel_hi:[0,1]
	v_pk_mul_f32 v[84:85], v[142:143], v[84:85] op_sel_hi:[0,1]
	v_pk_fma_f32 v[84:85], v[18:19], v[84:85], v[128:129]
	v_pk_fma_f32 v[104:105], v[16:17], v[104:105], v[106:107]
	v_cvt_pk_bf16_f32 v107, v84, v85
	v_cvt_pk_bf16_f32 v106, v104, v105
	global_store_dwordx2 v[144:145], v[106:107], off offset:2048
	v_lshlrev_b32_e32 v106, 16, v82
	v_and_b32_e32 v107, 0xffff0000, v82
	v_lshlrev_b32_e32 v82, 16, v83
	v_and_b32_e32 v83, 0xffff0000, v83
	v_pk_mul_f32 v[106:107], v[142:143], v[106:107] op_sel_hi:[0,1]
	v_pk_mul_f32 v[82:83], v[142:143], v[82:83] op_sel_hi:[0,1]
	v_pk_fma_f32 v[82:83], v[22:23], v[82:83], v[132:133]
	v_pk_fma_f32 v[110:111], v[20:21], v[106:107], v[130:131]
	v_cvt_pk_bf16_f32 v107, v82, v83
	v_cvt_pk_bf16_f32 v106, v110, v111
	global_store_dwordx2 v[144:145], v[106:107], off offset:2560
	v_lshlrev_b32_e32 v106, 16, v80
	v_and_b32_e32 v107, 0xffff0000, v80
	v_lshlrev_b32_e32 v80, 16, v81
	v_and_b32_e32 v81, 0xffff0000, v81
	v_pk_mul_f32 v[106:107], v[142:143], v[106:107] op_sel_hi:[0,1]
	v_pk_mul_f32 v[80:81], v[142:143], v[80:81] op_sel_hi:[0,1]
	v_pk_fma_f32 v[80:81], v[26:27], v[80:81], v[136:137]
	v_pk_fma_f32 v[112:113], v[24:25], v[106:107], v[134:135]
	v_cvt_pk_bf16_f32 v107, v80, v81
	v_cvt_pk_bf16_f32 v106, v112, v113
	global_store_dwordx2 v[144:145], v[106:107], off offset:3072
	v_lshlrev_b32_e32 v106, 16, v78
	v_and_b32_e32 v107, 0xffff0000, v78
	v_lshlrev_b32_e32 v78, 16, v79
	v_and_b32_e32 v79, 0xffff0000, v79
; __device__ __forceinline__ unsigned pk2(float lo, float hi) { return cvtpk_(lo, hi); }
; template <bool XIB, bool XOB> __device__ __forceinline__ void rowpass(const bf16_t* Y, const float* part, const void* Xin, void* Xout, const float* g_post, const float* g_pre, bf16_t* Hout, int gw, int ngw, int lane_) {
;     ...
;             s += (v[j][0] * v[j][0] + v[j][1] * v[j][1]) + (v[j][2] * v[j][2] + v[j][3] * v[j][3]);
;         }
;         if (Hout) {
;             const float r2 = rsqrtf(wave_sum(s) * (1.0f / DM) + RMS_EPS);
;             const f32x4* gq = (const f32x4*)g_pre + lane; u32x2* o8 = (u32x2*)(Hout + (size_t)row * DM) + lane;
; #pragma unroll
;             for (int j = 0; j < 8; ++j) { const f32x4 g = gq[64 * j]; u32x2 w; w.x = pk2(v[j][0] * r2 * g[0], v[j][1] * r2 * g[1]); w.y = pk2(v[j][2] * r2 * g[2], v[j][3] * r2 * g[3]); o8[64 * j] = w; }
;         }
	v_pk_mul_f32 v[108:109], v[142:143], v[106:107] op_sel_hi:[0,1]
	v_pk_mul_f32 v[78:79], v[142:143], v[78:79] op_sel_hi:[0,1]
	v_pk_fma_f32 v[106:107], v[30:31], v[78:79], v[140:141]
	v_pk_fma_f32 v[108:109], v[28:29], v[108:109], v[138:139]
	v_cvt_pk_bf16_f32 v79, v106, v107
	v_cvt_pk_bf16_f32 v78, v108, v109
	v_mov_b32_e32 v122, v97
	v_mov_b32_e32 v123, v99
	global_store_dwordx2 v[144:145], v[78:79], off offset:3584
	v_mov_b32_e32 v78, v96
	v_mov_b32_e32 v79, v98
	v_pk_mul_f32 v[122:123], v[122:123], v[122:123]
	v_mov_b32_e32 v124, v94
	v_mov_b32_e32 v125, v90
	v_pk_fma_f32 v[78:79], v[78:79], v[78:79], v[122:123]
	v_mov_b32_e32 v122, v95
	v_mov_b32_e32 v123, v91
	v_pk_mul_f32 v[124:125], v[124:125], v[124:125]
	s_add_u32 s6, s6, s8
	v_pk_fma_f32 v[122:123], v[122:123], v[122:123], v[124:125]
	v_pk_mul_f32 v[124:125], v[88:89], v[88:89]
	v_pk_add_f32 v[78:79], v[78:79], v[122:123]
	v_pk_mul_f32 v[122:123], v[100:101], v[100:101]
	v_mov_b32_e32 v127, v125
	v_mov_b32_e32 v126, v122
	v_pk_mov_b32 v[122:123], v[122:123], v[124:125] op_sel:[1,0]
	v_pk_add_f32 v[78:79], v[78:79], v[78:79] op_sel_hi:[0,1]
	v_pk_add_f32 v[126:127], v[126:127], v[122:123]
	v_mul_f32_e32 v78, v102, v102
	v_pk_fma_f32 v[128:129], v[102:103], v[102:103], v[78:79] op_sel_hi:[1,1,0]
	v_mul_f32_e32 v78, v86, v86
	v_pk_add_f32 v[126:127], v[126:127], v[126:127] op_sel_hi:[0,1]
	v_pk_fma_f32 v[130:131], v[86:87], v[86:87], v[78:79] op_sel_hi:[1,1,0]
	v_mul_f32_e32 v128, v104, v104
	v_mul_f32_e32 v130, v105, v105
	v_mul_f32_e32 v126, v85, v85
	v_mul_f32_e32 v78, v84, v84
	v_pk_add_f32 v[128:129], v[128:129], v[130:131]
	v_pk_add_f32 v[78:79], v[126:127], v[78:79]
	v_pk_mul_f32 v[126:127], v[110:111], v[110:111]
	v_pk_add_f32 v[78:79], v[128:129], v[78:79]
	v_pk_mul_f32 v[128:129], v[82:83], v[82:83]
	v_pk_add_f32 v[78:79], v[78:79], v[78:79] op_sel_hi:[0,1]
	v_mov_b32_e32 v130, v126
	v_mov_b32_e32 v131, v129
	v_pk_mov_b32 v[126:127], v[126:127], v[128:129] op_sel:[1,0]
	v_mul_f32_e32 v78, v112, v112
	v_pk_add_f32 v[126:127], v[130:131], v[126:127]
	v_pk_fma_f32 v[128:129], v[112:113], v[112:113], v[78:79] op_sel_hi:[1,1,0]
	v_mul_f32_e32 v78, v80, v80
	v_pk_add_f32 v[126:127], v[126:127], v[126:127] op_sel_hi:[0,1]
	v_pk_fma_f32 v[130:131], v[80:81], v[80:81], v[78:79] op_sel_hi:[1,1,0]
	v_mul_f32_e32 v128, v108, v108
	v_mul_f32_e32 v130, v109, v109
	v_mul_f32_e32 v126, v107, v107
	v_mul_f32_e32 v78, v106, v106
	v_pk_add_f32 v[128:129], v[128:129], v[130:131]
	v_pk_add_f32 v[78:79], v[126:127], v[78:79]
	s_addc_u32 s7, s7, s9
	v_pk_add_f32 v[78:79], v[128:129], v[78:79]
	s_add_u32 s14, s14, s8
	v_add_f32_e32 v78, v78, v79
	ds_bpermute_b32 v79, v114, v78
	s_addc_u32 s15, s15, s9
	s_add_u32 s16, s16, s8
	v_lshl_add_u64 v[44:45], v[44:45], 0, s[18:19]
	s_addc_u32 s17, s17, s9
	s_waitcnt lgkmcnt(0)
	v_add_f32_e32 v78, v78, v79
	ds_bpermute_b32 v79, v115, v78
	s_waitcnt lgkmcnt(0)
	v_add_f32_e32 v78, v78, v79
	ds_bpermute_b32 v79, v116, v78
	s_waitcnt lgkmcnt(0)
	v_add_f32_e32 v78, v78, v79
	ds_bpermute_b32 v79, v117, v78
	s_waitcnt lgkmcnt(0)
	v_add_f32_e32 v78, v78, v79
	ds_bpermute_b32 v79, v118, v78
	s_waitcnt lgkmcnt(0)
	v_add_f32_e32 v78, v78, v79
	ds_bpermute_b32 v79, v119, v78
	s_waitcnt lgkmcnt(0)
	v_add_f32_e32 v78, v78, v79
	v_fmamk_f32 v78, v78, 0x3a000000, v120
	v_mul_f32_e32 v79, 0x4b800000, v78
	v_cmp_gt_f32_e32 vcc, s2, v78
	s_nop 1
	v_cndmask_b32_e32 v78, v78, v79, vcc
	v_rsq_f32_e32 v78, v78
	s_nop 0
	v_mul_f32_e32 v79, 0x45800000, v78
	v_cndmask_b32_e32 v126, v78, v79, vcc
	v_pk_mul_f32 v[78:79], v[96:97], v[126:127] op_sel_hi:[1,0]
	v_pk_mul_f32 v[94:95], v[94:95], v[126:127] op_sel_hi:[1,0]
	v_pk_mul_f32 v[78:79], v[200:201], v[78:79]
	v_pk_mul_f32 v[94:95], v[202:203], v[94:95]
	v_add_co_u32_e32 v128, vcc, s5, v92
	v_cvt_pk_bf16_f32 v78, v78, v79
	v_cvt_pk_bf16_f32 v79, v94, v95
	v_addc_co_u32_e32 v129, vcc, 0, v93, vcc
	global_store_dwordx2 v[128:129], v[78:79], off
	v_pk_mul_f32 v[78:79], v[98:99], v[126:127] op_sel_hi:[1,0]
	v_pk_mul_f32 v[90:91], v[90:91], v[126:127] op_sel_hi:[1,0]
	v_pk_mul_f32 v[88:89], v[88:89], v[126:127] op_sel_hi:[1,0]
	v_pk_mul_f32 v[86:87], v[86:87], v[126:127] op_sel_hi:[1,0]
	v_pk_mul_f32 v[84:85], v[84:85], v[126:127] op_sel_hi:[1,0]
	v_pk_mul_f32 v[82:83], v[82:83], v[126:127] op_sel_hi:[1,0]
	v_pk_mul_f32 v[80:81], v[80:81], v[126:127] op_sel_hi:[1,0]
	v_pk_mul_f32 v[108:109], v[108:109], v[126:127] op_sel_hi:[1,0]
	v_pk_mul_f32 v[106:107], v[106:107], v[126:127] op_sel_hi:[1,0]
	s_andn2_b64 vcc, exec, s[20:21]
	v_pk_mul_f32 v[78:79], v[204:205], v[78:79]
	v_pk_mul_f32 v[90:91], v[206:207], v[90:91]
	v_cvt_pk_bf16_f32 v78, v78, v79
	v_cvt_pk_bf16_f32 v79, v90, v91
	global_store_dwordx2 v[128:129], v[78:79], off offset:512
	v_pk_mul_f32 v[78:79], v[100:101], v[126:127] op_sel_hi:[1,0]
	v_pk_mul_f32 v[78:79], v[208:209], v[78:79]
	v_pk_mul_f32 v[88:89], v[210:211], v[88:89]
	v_cvt_pk_bf16_f32 v78, v78, v79
	v_cvt_pk_bf16_f32 v79, v88, v89
	global_store_dwordx2 v[128:129], v[78:79], off offset:1024
	v_pk_mul_f32 v[78:79], v[102:103], v[126:127] op_sel_hi:[1,0]
	v_pk_mul_f32 v[78:79], v[212:213], v[78:79]
	v_pk_mul_f32 v[86:87], v[214:215], v[86:87]
	v_cvt_pk_bf16_f32 v78, v78, v79
	v_cvt_pk_bf16_f32 v79, v86, v87
	global_store_dwordx2 v[128:129], v[78:79], off offset:1536
	v_pk_mul_f32 v[78:79], v[104:105], v[126:127] op_sel_hi:[1,0]
	v_pk_mul_f32 v[78:79], v[216:217], v[78:79]
	v_pk_mul_f32 v[84:85], v[218:219], v[84:85]
	v_cvt_pk_bf16_f32 v78, v78, v79
	v_cvt_pk_bf16_f32 v79, v84, v85
	global_store_dwordx2 v[128:129], v[78:79], off offset:2048
	v_pk_mul_f32 v[78:79], v[110:111], v[126:127] op_sel_hi:[1,0]
	v_pk_mul_f32 v[78:79], v[220:221], v[78:79]
	v_pk_mul_f32 v[82:83], v[222:223], v[82:83]
	v_cvt_pk_bf16_f32 v78, v78, v79
	v_cvt_pk_bf16_f32 v79, v82, v83
	global_store_dwordx2 v[128:129], v[78:79], off offset:2560
	v_pk_mul_f32 v[78:79], v[112:113], v[126:127] op_sel_hi:[1,0]
	v_pk_mul_f32 v[78:79], v[224:225], v[78:79]
	v_pk_mul_f32 v[80:81], v[226:227], v[80:81]
	v_cvt_pk_bf16_f32 v78, v78, v79
	v_cvt_pk_bf16_f32 v79, v80, v81
	global_store_dwordx2 v[128:129], v[78:79], off offset:3072
	v_pk_mul_f32 v[108:109], v[228:229], v[108:109]
	v_pk_mul_f32 v[106:107], v[230:231], v[106:107]
	v_cvt_pk_bf16_f32 v108, v108, v109
	v_cvt_pk_bf16_f32 v109, v106, v107
	global_store_dwordx2 v[128:129], v[108:109], off offset:3584
	s_waitcnt vmcnt(16)
	v_mov_b64_e32 v[98:99], v[66:67]
	v_mov_b64_e32 v[96:97], v[68:69]
	v_mov_b64_e32 v[100:101], v[62:63]
	v_mov_b64_e32 v[94:95], v[48:49]
	v_mov_b64_e32 v[102:103], v[56:57]
	v_mov_b64_e32 v[92:93], v[72:73]
	v_mov_b64_e32 v[104:105], v[52:53]
	v_mov_b64_e32 v[90:91], v[54:55]
	v_mov_b64_e32 v[110:111], v[50:51]
	v_mov_b64_e32 v[88:89], v[58:59]
	v_mov_b64_e32 v[112:113], v[46:47]
	v_mov_b64_e32 v[86:87], v[60:61]
	v_mov_b64_e32 v[84:85], v[64:65]
	v_mov_b64_e32 v[82:83], v[70:71]
	v_mov_b64_e32 v[80:81], v[74:75]
	v_mov_b64_e32 v[78:79], v[76:77]
	v_mov_b32_e32 v106, v121
	s_cbranch_vccz .LBB0_923
